# v82 + EpiLn step 1: residual rows of the last blocks also prefetched (P7 blocks 6,7 into the registers of consumed blocks; P10 block 7)
# baseline (speedup 1.0000x reference)
;     __device__ __forceinline__ void fused(f32x4 (&acc)[2][2][4][2], const Unit& u, int wr, int wc, int fr, int fq, PG8_LAS unsigned char* lds, int wid, int lane) const {
;     ...
; #pragma unroll
;         for (int ai = 0; ai < 2; ++ai)
; #pragma unroll
;             for (int m = 0; m < 4; ++m) {
;                 const int rl = ai * 128 + wr * 64 + m * 16 + fr;
;                 const size_t roff = (size_t)(u.pm * 256 + rl) * 1024 + u.pn * 256 + wc * 32 + fq * 8;
;                 float s1 = 0.f, s2 = 0.f;
; #pragma unroll
;                 for (int bj = 0; bj < 2; ++bj) {
;                     float x[8];
;                     if (RES_BF16) ld8f((const bfu*)res + roff + bj * 128, x);
;                     else ld8f32((const float*)res + roff + bj * 128, x);
; #pragma unroll
;                     for (int n = 0; n < 2; ++n) {
;                         f32x4 v = acc[ai][bj][m][n];
;                         v[0] += ALPHA * x[4 * n]; v[1] += ALPHA * x[4 * n + 1]; v[2] += ALPHA * x[4 * n + 2]; v[3] += ALPHA * x[4 * n + 3];
;                         acc[ai][bj][m][n] = v;
;                         s1 += (v[0] + v[1]) + (v[2] + v[3]); s2 += (v[0] * v[0] + v[1] * v[1]) + (v[2] * v[2] + v[3] * v[3]);
;                     }
;                 }
;                 s1 += __shfl_xor(s1, 16); s1 += __shfl_xor(s1, 32); s2 += __shfl_xor(s2, 16); s2 += __shfl_xor(s2, 32);
.LBB0_1048:
	s_add_u32 s22, s66, 0x38b00000
	s_addc_u32 s23, s67, 0
	s_lshl_b32 s19, s18, 8
	v_add_u32_e32 v142, s19, v129
	s_lshl_b32 s8, s20, 8
	v_ashrrev_i32_e32 v143, 31, v142
	v_readlane_b32 s28, v252, 8
	s_ashr_i32 s9, s8, 31
	v_lshlrev_b64 v[142:143], 11, v[142:143]
	v_readlane_b32 s29, v252, 9
	s_lshl_b64 s[26:27], s[8:9], 1
	s_mov_b32 s25, 0
	v_lshl_add_u64 v[144:145], s[28:29], 0, v[142:143]
	v_lshl_add_u64 v[144:145], v[144:145], 0, s[26:27]
	s_lshl_b32 s24, s11, 6
	v_lshl_add_u64 v[144:145], v[144:145], 0, s[24:25]
	v_mov_b32_e32 v141, 0
	v_lshl_add_u64 v[144:145], v[144:145], 0, v[140:141]
	s_barrier
	global_load_dwordx4 v[146:149], v[144:145], off
	global_load_dwordx4 v[150:153], v[144:145], off offset:256
	s_mov_b64 s[98:99], 0x8000
	v_lshl_add_u64 v[250:251], v[144:145], 0, s[98:99]
	global_load_dwordx4 v[210:213], v[250:251], off
	global_load_dwordx4 v[214:217], v[250:251], off offset:256
	s_mov_b64 s[98:99], 0x10000
	v_lshl_add_u64 v[250:251], v[144:145], 0, s[98:99]
	global_load_dwordx4 v[218:221], v[250:251], off
	global_load_dwordx4 v[222:225], v[250:251], off offset:256
	s_mov_b64 s[98:99], 0x18000
	v_lshl_add_u64 v[250:251], v[144:145], 0, s[98:99]
	global_load_dwordx4 v[226:229], v[250:251], off
	global_load_dwordx4 v[230:233], v[250:251], off offset:256
	s_mov_b64 s[98:99], 0x40000
	v_lshl_add_u64 v[250:251], v[144:145], 0, s[98:99]
	global_load_dwordx4 v[234:237], v[250:251], off
	global_load_dwordx4 v[238:241], v[250:251], off offset:256
	s_mov_b64 s[98:99], 0x48000
	v_lshl_add_u64 v[250:251], v[144:145], 0, s[98:99]
	global_load_dwordx4 v[242:245], v[250:251], off
	global_load_dwordx4 v[246:249], v[250:251], off offset:256
	v_readlane_b32 s98, v252, 6
	v_readlane_b32 s99, v252, 7
	s_nop 3
	s_and_saveexec_b64 s[100:101], s[98:99]
	s_cbranch_execz .Lpub_skip_p7
	s_lshl_b32 s98, s2, 2
	s_andn2_b32 s98, s98, 63
	s_lshl_b32 s98, s98, 2
	s_add_u32 s98, s3, s98
	s_addc_u32 s99, s33, 0
	v_mov_b32_e32 v253, 0
	v_mov_b32_e32 v254, 1
	global_atomic_add v253, v254, s[98:99]
.Lpub_skip_p7:
	s_mov_b64 exec, s[100:101]
	s_mov_b64 s[98:99], 0x50000
	v_lshl_add_u64 v[250:251], v[144:145], 0, s[98:99]
	v_mbcnt_lo_u32_b32 v144, -1, 0
	v_mbcnt_hi_u32_b32 v154, -1, v144
	v_and_b32_e32 v145, 64, v154
	v_or_b32_e32 v178, 16, v129
	v_xor_b32_e32 v155, 16, v154
	v_add_u32_e32 v157, 64, v145
	v_xor_b32_e32 v156, 32, v154
	v_add_u32_e32 v144, s19, v178
	v_cmp_lt_i32_e32 vcc, v155, v157
	v_ashrrev_i32_e32 v145, 31, v144
	v_lshlrev_b64 v[144:145], 11, v[144:145]
	v_cndmask_b32_e32 v155, v154, v155, vcc
	v_cmp_lt_i32_e32 vcc, v156, v157
	v_lshlrev_b32_e32 v181, 2, v155
	s_mov_b32 s6, 0x3f9837f0
	v_cndmask_b32_e32 v154, v154, v156, vcc
	v_lshlrev_b32_e32 v180, 2, v154
	v_lshl_add_u64 v[154:155], s[28:29], 0, v[144:145]
	v_lshl_add_u64 v[154:155], v[154:155], 0, s[26:27]
	v_lshl_add_u64 v[154:155], v[154:155], 0, s[24:25]
	v_lshl_add_u64 v[158:159], v[154:155], 0, v[140:141]
	s_waitcnt vmcnt(0)
	v_mov_b64_e32 v[154:155], v[210:211]
	v_mov_b64_e32 v[156:157], v[212:213]
	s_nop 0
	v_mov_b64_e32 v[158:159], v[214:215]
	v_mov_b64_e32 v[160:161], v[216:217]
	v_or_b32_e32 v179, 32, v129
	v_lshl_add_u32 v177, v172, 3, 0
	v_cmp_eq_u32_e32 vcc, 0, v176
	s_waitcnt vmcnt(0)
	v_lshlrev_b32_e32 v162, 16, v146
	v_and_b32_e32 v163, 0xffff0000, v146
	v_lshlrev_b32_e32 v164, 16, v147
	v_and_b32_e32 v165, 0xffff0000, v147
	v_lshlrev_b32_e32 v166, 16, v148
	v_and_b32_e32 v167, 0xffff0000, v148
	v_lshlrev_b32_e32 v148, 16, v149
	v_and_b32_e32 v149, 0xffff0000, v149
	v_lshlrev_b32_e32 v168, 16, v150
	v_and_b32_e32 v169, 0xffff0000, v150
	v_lshlrev_b32_e32 v150, 16, v151
	v_and_b32_e32 v151, 0xffff0000, v151
	v_lshlrev_b32_e32 v170, 16, v152
	v_and_b32_e32 v171, 0xffff0000, v152
	v_lshlrev_b32_e32 v152, 16, v153
	v_and_b32_e32 v153, 0xffff0000, v153
	v_pk_fma_f32 v[146:147], v[162:163], s[6:7], v[124:125] op_sel_hi:[1,0,1]
	v_pk_fma_f32 v[124:125], v[164:165], s[6:7], v[126:127] op_sel_hi:[1,0,1]
	v_pk_fma_f32 v[126:127], v[166:167], s[6:7], v[120:121] op_sel_hi:[1,0,1]
	v_pk_fma_f32 v[122:123], v[148:149], s[6:7], v[122:123] op_sel_hi:[1,0,1]
	v_pk_fma_f32 v[120:121], v[168:169], s[6:7], v[116:117] op_sel_hi:[1,0,1]
	v_pk_fma_f32 v[116:117], v[150:151], s[6:7], v[118:119] op_sel_hi:[1,0,1]
	v_pk_fma_f32 v[118:119], v[170:171], s[6:7], v[112:113] op_sel_hi:[1,0,1]
	v_pk_fma_f32 v[112:113], v[152:153], s[6:7], v[114:115] op_sel_hi:[1,0,1]
	v_pk_add_f32 v[114:115], v[146:147], v[146:147] op_sel:[0,1] op_sel_hi:[1,0]
	v_pk_add_f32 v[148:149], v[124:125], v[124:125] op_sel:[0,1] op_sel_hi:[1,0]
	v_pk_mul_f32 v[150:151], v[146:147], v[146:147]
	v_pk_mul_f32 v[152:153], v[124:125], v[124:125]
	v_pk_mul_f32 v[162:163], v[126:127], v[126:127]
	v_mul_f32_e32 v164, v122, v122
	v_mov_b32_e32 v182, v126
	v_mov_b32_e32 v184, v122
	v_pk_fma_f32 v[164:165], v[122:123], v[122:123], v[164:165] op_sel_hi:[1,1,0]
	v_mov_b32_e32 v183, v150
	v_mov_b32_e32 v150, v127
	v_mov_b32_e32 v185, v152
	v_mov_b32_e32 v152, v123
	v_mov_b32_e32 v115, v162
	v_mov_b32_e32 v149, v163
	v_pk_add_f32 v[150:151], v[182:183], v[150:151]
	v_pk_add_f32 v[152:153], v[184:185], v[152:153]
	v_pk_add_f32 v[114:115], v[114:115], v[148:149]
	v_mov_b32_e32 v164, v141
	v_pk_mul_f32 v[166:167], v[120:121], v[120:121]
	v_pk_mul_f32 v[168:169], v[116:117], v[116:117]
	v_pk_add_f32 v[150:151], v[150:151], v[152:153]
	v_pk_add_f32 v[114:115], v[114:115], v[164:165]
	v_mov_b32_e32 v188, v120
	v_mov_b32_e32 v189, v166
	v_mov_b32_e32 v166, v121
	v_pk_add_f32 v[114:115], v[150:151], v[114:115]
	v_mov_b32_e32 v150, v116
	v_mov_b32_e32 v151, v168
	v_mov_b32_e32 v168, v117
	v_pk_add_f32 v[148:149], v[188:189], v[166:167]
	v_pk_add_f32 v[150:151], v[150:151], v[168:169]
	v_pk_mul_f32 v[170:171], v[118:119], v[118:119]
	v_pk_mul_f32 v[174:175], v[112:113], v[112:113]
	v_pk_add_f32 v[148:149], v[148:149], v[150:151]
	v_mov_b32_e32 v150, v112
	v_pk_add_f32 v[114:115], v[114:115], v[148:149]
	v_mov_b32_e32 v148, v118
	v_mov_b32_e32 v149, v170
	v_mov_b32_e32 v170, v119
	v_mov_b32_e32 v151, v174
	v_mov_b32_e32 v174, v113
	v_pk_add_f32 v[148:149], v[148:149], v[170:171]
	v_pk_add_f32 v[150:151], v[150:151], v[174:175]
	s_lshl_b32 s7, s11, 3
	v_pk_add_f32 v[148:149], v[148:149], v[150:151]
	s_add_i32 s7, s7, 0
	v_pk_add_f32 v[114:115], v[114:115], v[148:149]
	ds_bpermute_b32 v148, v181, v114
	ds_bpermute_b32 v149, v181, v115
	v_lshlrev_b32_e32 v168, 16, v156
	v_and_b32_e32 v169, 0xffff0000, v156
	v_lshlrev_b32_e32 v156, 16, v157
	v_and_b32_e32 v157, 0xffff0000, v157
	s_waitcnt lgkmcnt(0)
; #define PG8_LAS __attribute__((address_space(3)))
;     __device__ __forceinline__ void fused(f32x4 (&acc)[2][2][4][2], const Unit& u, int wr, int wc, int fr, int fq, PG8_LAS unsigned char* lds, int wid, int lane) const {
;     ...
;         for (int ai = 0; ai < 2; ++ai)
; #pragma unroll
;             for (int m = 0; m < 4; ++m) {
;                 const int rl = ai * 128 + wr * 64 + m * 16 + fr;
;                 const size_t roff = (size_t)(u.pm * 256 + rl) * 1024 + u.pn * 256 + wc * 32 + fq * 8;
;                 float s1 = 0.f, s2 = 0.f;
; #pragma unroll
;                 for (int bj = 0; bj < 2; ++bj) {
;                     float x[8];
;                     if (RES_BF16) ld8f((const bfu*)res + roff + bj * 128, x);
;                     else ld8f32((const float*)res + roff + bj * 128, x);
; #pragma unroll
;                     for (int n = 0; n < 2; ++n) {
;                         f32x4 v = acc[ai][bj][m][n];
;                         v[0] += ALPHA * x[4 * n]; v[1] += ALPHA * x[4 * n + 1]; v[2] += ALPHA * x[4 * n + 2]; v[3] += ALPHA * x[4 * n + 3];
;                         acc[ai][bj][m][n] = v;
;                         s1 += (v[0] + v[1]) + (v[2] + v[3]); s2 += (v[0] * v[0] + v[1] * v[1]) + (v[2] * v[2] + v[3] * v[3]);
;                     }
;                 }
;                 s1 += __shfl_xor(s1, 16); s1 += __shfl_xor(s1, 32); s2 += __shfl_xor(s2, 16); s2 += __shfl_xor(s2, 32);
;                 {
;                     PG8_LAS float* pd = (fq == 0) ? P + (rl * 4 + wc) * 2 : (PG8_LAS float*)(lds + 12288) + tid * 2;
;                     pd[0] = s1; pd[1] = s2;
;                 }
	v_pk_add_f32 v[162:163], v[114:115], v[148:149]
	v_add_u32_e32 v148, s19, v179
	v_ashrrev_i32_e32 v149, 31, v148
	v_lshlrev_b64 v[148:149], 11, v[148:149]
	v_lshl_add_u64 v[150:151], s[28:29], 0, v[148:149]
	v_lshl_add_u64 v[150:151], v[150:151], 0, s[26:27]
	v_lshl_add_u64 v[150:151], v[150:151], 0, s[24:25]
	v_lshl_add_u64 v[166:167], v[150:151], 0, v[140:141]
	v_mov_b64_e32 v[150:151], v[218:219]
	v_mov_b64_e32 v[152:153], v[220:221]
	v_lshlrev_b32_e32 v114, 16, v154
	v_and_b32_e32 v115, 0xffff0000, v154
	v_lshlrev_b32_e32 v154, 16, v155
	v_and_b32_e32 v155, 0xffff0000, v155
	v_pk_fma_f32 v[114:115], v[114:115], s[6:7], v[108:109] op_sel_hi:[1,0,1]
	v_pk_fma_f32 v[108:109], v[154:155], s[6:7], v[110:111] op_sel_hi:[1,0,1]
	v_pk_fma_f32 v[106:107], v[156:157], s[6:7], v[106:107] op_sel_hi:[1,0,1]
	v_mov_b64_e32 v[154:155], v[222:223]
	v_mov_b64_e32 v[156:157], v[224:225]
	global_load_dwordx4 v[210:213], v[250:251], off
	global_load_dwordx4 v[214:217], v[250:251], off offset:256
	s_mov_b64 s[98:99], 0x8000
	v_lshl_add_u64 v[250:251], v[250:251], 0, s[98:99]
	global_load_dwordx4 v[218:221], v[250:251], off
	global_load_dwordx4 v[222:225], v[250:251], off offset:256
	v_pk_fma_f32 v[110:111], v[168:169], s[6:7], v[104:105] op_sel_hi:[1,0,1]
	v_mul_f32_e32 v104, v106, v106
	v_pk_fma_f32 v[190:191], v[106:107], v[106:107], v[104:105] op_sel_hi:[1,1,0]
	v_lshlrev_b32_e32 v104, 16, v158
	v_and_b32_e32 v105, 0xffff0000, v158
	v_pk_add_f32 v[170:171], v[114:115], v[114:115] op_sel:[0,1] op_sel_hi:[1,0]
	v_pk_add_f32 v[174:175], v[108:109], v[108:109] op_sel:[0,1] op_sel_hi:[1,0]
	v_pk_mul_f32 v[168:169], v[110:111], v[110:111]
	v_lshlrev_b32_e32 v158, 16, v159
	v_and_b32_e32 v159, 0xffff0000, v159
	v_pk_fma_f32 v[100:101], v[104:105], s[6:7], v[100:101] op_sel_hi:[1,0,1]
	v_pk_fma_f32 v[102:103], v[158:159], s[6:7], v[102:103] op_sel_hi:[1,0,1]
	v_pk_mul_f32 v[158:159], v[100:101], v[100:101]
	v_mov_b32_e32 v171, v168
	v_mov_b32_e32 v175, v169
	v_pk_mul_f32 v[184:185], v[114:115], v[114:115]
	v_lshlrev_b32_e32 v192, 16, v160
	v_and_b32_e32 v193, 0xffff0000, v160
	v_pk_mul_f32 v[166:167], v[102:103], v[102:103]
	v_pk_add_f32 v[168:169], v[170:171], v[174:175]
	v_mov_b32_e32 v170, v100
	v_mov_b32_e32 v171, v158
	v_mov_b32_e32 v158, v101
	v_pk_mul_f32 v[188:189], v[108:109], v[108:109]
	v_lshlrev_b32_e32 v160, 16, v161
	v_and_b32_e32 v161, 0xffff0000, v161
	v_pk_fma_f32 v[104:105], v[192:193], s[6:7], v[96:97] op_sel_hi:[1,0,1]
	v_mov_b32_e32 v192, v110
	v_mov_b32_e32 v193, v184
	v_mov_b32_e32 v184, v111
	v_pk_add_f32 v[158:159], v[170:171], v[158:159]
	v_mov_b32_e32 v170, v102
	v_mov_b32_e32 v171, v166
	v_mov_b32_e32 v166, v103
	v_pk_fma_f32 v[96:97], v[160:161], s[6:7], v[98:99] op_sel_hi:[1,0,1]
	v_pk_mul_f32 v[98:99], v[104:105], v[104:105]
	v_pk_add_f32 v[184:185], v[192:193], v[184:185]
	v_mov_b32_e32 v192, v106
	v_mov_b32_e32 v193, v188
	v_mov_b32_e32 v188, v107
	v_pk_add_f32 v[166:167], v[170:171], v[166:167]
	v_pk_mul_f32 v[160:161], v[96:97], v[96:97]
	v_pk_add_f32 v[188:189], v[192:193], v[188:189]
	v_mov_b32_e32 v190, v141
	v_pk_add_f32 v[158:159], v[158:159], v[166:167]
	v_mov_b32_e32 v166, v104
	v_mov_b32_e32 v167, v98
	v_mov_b32_e32 v98, v105
	v_pk_add_f32 v[184:185], v[184:185], v[188:189]
	v_pk_add_f32 v[168:169], v[168:169], v[190:191]
	v_pk_add_f32 v[98:99], v[166:167], v[98:99]
	v_mov_b32_e32 v166, v96
	v_mov_b32_e32 v167, v160
	v_mov_b32_e32 v160, v97
	v_pk_add_f32 v[168:169], v[184:185], v[168:169]
	v_pk_add_f32 v[160:161], v[166:167], v[160:161]
	v_pk_add_f32 v[158:159], v[168:169], v[158:159]
	v_pk_add_f32 v[98:99], v[98:99], v[160:161]
	ds_bpermute_b32 v164, v180, v162
	v_pk_add_f32 v[98:99], v[158:159], v[98:99]
	ds_bpermute_b32 v165, v180, v163
	ds_bpermute_b32 v158, v181, v98
	ds_bpermute_b32 v159, v181, v99
	v_or_b32_e32 v182, 48, v129
	v_add_u32_e32 v183, 0x3000, v177
	s_waitcnt lgkmcnt(2)
	v_pk_add_f32 v[162:163], v[162:163], v[164:165]
	v_lshl_add_u32 v160, v129, 5, s7
	s_waitcnt lgkmcnt(0)
	v_pk_add_f32 v[164:165], v[98:99], v[158:159]
	v_add_u32_e32 v98, s19, v182
	v_ashrrev_i32_e32 v99, 31, v98
	v_lshlrev_b64 v[98:99], 11, v[98:99]
	v_lshl_add_u64 v[158:159], s[28:29], 0, v[98:99]
	v_lshl_add_u64 v[158:159], v[158:159], 0, s[26:27]
	v_lshl_add_u64 v[158:159], v[158:159], 0, s[24:25]
	v_lshl_add_u64 v[170:171], v[158:159], 0, v[140:141]
	v_cndmask_b32_e32 v200, v183, v160, vcc
	v_mov_b64_e32 v[158:159], v[226:227]
	v_mov_b64_e32 v[160:161], v[228:229]
	v_lshlrev_b32_e32 v184, 16, v152
	v_and_b32_e32 v185, 0xffff0000, v152
	v_lshlrev_b32_e32 v152, 16, v153
	v_and_b32_e32 v153, 0xffff0000, v153
	v_lshlrev_b32_e32 v168, 16, v150
	v_and_b32_e32 v169, 0xffff0000, v150
	v_lshlrev_b32_e32 v174, 16, v151
	v_and_b32_e32 v175, 0xffff0000, v151
	v_pk_fma_f32 v[90:91], v[152:153], s[6:7], v[90:91] op_sel_hi:[1,0,1]
	v_pk_fma_f32 v[150:151], v[168:169], s[6:7], v[92:93] op_sel_hi:[1,0,1]
	v_pk_fma_f32 v[92:93], v[174:175], s[6:7], v[94:95] op_sel_hi:[1,0,1]
	v_pk_fma_f32 v[94:95], v[184:185], s[6:7], v[88:89] op_sel_hi:[1,0,1]
	v_mul_f32_e32 v88, v90, v90
	v_pk_fma_f32 v[184:185], v[90:91], v[90:91], v[88:89] op_sel_hi:[1,1,0]
	v_lshlrev_b32_e32 v88, 16, v154
	v_and_b32_e32 v89, 0xffff0000, v154
	v_lshlrev_b32_e32 v192, 16, v155
	v_and_b32_e32 v193, 0xffff0000, v155
	v_lshlrev_b32_e32 v196, 16, v156
	v_and_b32_e32 v197, 0xffff0000, v156
	v_lshlrev_b32_e32 v198, 16, v157
	v_and_b32_e32 v199, 0xffff0000, v157
	v_mov_b64_e32 v[154:155], v[230:231]
	v_mov_b64_e32 v[156:157], v[232:233]
	v_pk_add_f32 v[168:169], v[150:151], v[150:151] op_sel:[0,1] op_sel_hi:[1,0]
	v_pk_add_f32 v[174:175], v[92:93], v[92:93] op_sel:[0,1] op_sel_hi:[1,0]
; #define PG8_LAS __attribute__((address_space(3)))
;     __device__ __forceinline__ void fused(f32x4 (&acc)[2][2][4][2], const Unit& u, int wr, int wc, int fr, int fq, PG8_LAS unsigned char* lds, int wid, int lane) const {
;     ...
;         for (int ai = 0; ai < 2; ++ai)
; #pragma unroll
;             for (int m = 0; m < 4; ++m) {
;                 const int rl = ai * 128 + wr * 64 + m * 16 + fr;
;                 const size_t roff = (size_t)(u.pm * 256 + rl) * 1024 + u.pn * 256 + wc * 32 + fq * 8;
;                 float s1 = 0.f, s2 = 0.f;
; #pragma unroll
;                 for (int bj = 0; bj < 2; ++bj) {
;                     float x[8];
;                     if (RES_BF16) ld8f((const bfu*)res + roff + bj * 128, x);
;                     else ld8f32((const float*)res + roff + bj * 128, x);
; #pragma unroll
;                     for (int n = 0; n < 2; ++n) {
;                         f32x4 v = acc[ai][bj][m][n];
;                         v[0] += ALPHA * x[4 * n]; v[1] += ALPHA * x[4 * n + 1]; v[2] += ALPHA * x[4 * n + 2]; v[3] += ALPHA * x[4 * n + 3];
;                         acc[ai][bj][m][n] = v;
;                         s1 += (v[0] + v[1]) + (v[2] + v[3]); s2 += (v[0] * v[0] + v[1] * v[1]) + (v[2] * v[2] + v[3] * v[3]);
;                     }
;                 }
;                 s1 += __shfl_xor(s1, 16); s1 += __shfl_xor(s1, 32); s2 += __shfl_xor(s2, 16); s2 += __shfl_xor(s2, 32);
;                 {
;                     PG8_LAS float* pd = (fq == 0) ? P + (rl * 4 + wc) * 2 : (PG8_LAS float*)(lds + 12288) + tid * 2;
;                     pd[0] = s1; pd[1] = s2;
;                 }
	v_pk_mul_f32 v[188:189], v[150:151], v[150:151]
	v_pk_mul_f32 v[152:153], v[94:95], v[94:95]
	v_pk_fma_f32 v[84:85], v[88:89], s[6:7], v[84:85] op_sel_hi:[1,0,1]
	v_pk_mul_f32 v[190:191], v[92:93], v[92:93]
	v_pk_fma_f32 v[86:87], v[192:193], s[6:7], v[86:87] op_sel_hi:[1,0,1]
	v_pk_mul_f32 v[170:171], v[84:85], v[84:85]
	v_pk_fma_f32 v[88:89], v[196:197], s[6:7], v[80:81] op_sel_hi:[1,0,1]
	v_pk_fma_f32 v[80:81], v[198:199], s[6:7], v[82:83] op_sel_hi:[1,0,1]
	v_mov_b32_e32 v198, v94
	v_mov_b32_e32 v199, v188
	v_mov_b32_e32 v188, v95
	v_mov_b32_e32 v169, v152
	v_mov_b32_e32 v175, v153
	v_pk_mul_f32 v[192:193], v[86:87], v[86:87]
	v_pk_add_f32 v[188:189], v[198:199], v[188:189]
	v_mov_b32_e32 v198, v90
	v_mov_b32_e32 v199, v190
	v_mov_b32_e32 v190, v91
	v_pk_add_f32 v[152:153], v[168:169], v[174:175]
	v_mov_b32_e32 v168, v84
	v_mov_b32_e32 v169, v170
	v_mov_b32_e32 v170, v85
	v_pk_add_f32 v[190:191], v[198:199], v[190:191]
	v_mov_b32_e32 v184, v141
	v_pk_add_f32 v[168:169], v[168:169], v[170:171]
	v_mov_b32_e32 v170, v86
	v_mov_b32_e32 v171, v192
	v_mov_b32_e32 v192, v87
	v_pk_add_f32 v[188:189], v[188:189], v[190:191]
	v_pk_add_f32 v[152:153], v[152:153], v[184:185]
	v_pk_add_f32 v[170:171], v[170:171], v[192:193]
	v_pk_mul_f32 v[82:83], v[88:89], v[88:89]
	v_pk_add_f32 v[152:153], v[188:189], v[152:153]
	v_pk_add_f32 v[168:169], v[168:169], v[170:171]
	v_pk_mul_f32 v[196:197], v[80:81], v[80:81]
	v_pk_add_f32 v[152:153], v[152:153], v[168:169]
	v_mov_b32_e32 v168, v88
	v_mov_b32_e32 v169, v82
	v_mov_b32_e32 v82, v89
	v_pk_add_f32 v[82:83], v[168:169], v[82:83]
	v_mov_b32_e32 v168, v80
	v_mov_b32_e32 v169, v196
	v_mov_b32_e32 v196, v81
	v_pk_add_f32 v[168:169], v[168:169], v[196:197]
	v_add_u32_e32 v188, 0x80, v129
	v_pk_add_f32 v[82:83], v[82:83], v[168:169]
	ds_bpermute_b32 v166, v180, v164
	v_pk_add_f32 v[82:83], v[152:153], v[82:83]
	ds_bpermute_b32 v152, v181, v82
	ds_bpermute_b32 v153, v181, v83
	ds_bpermute_b32 v167, v180, v165
	ds_write_b64 v200, v[162:163]
	v_lshl_add_u32 v162, v178, 5, s7
	v_cndmask_b32_e32 v189, v183, v162, vcc
	s_waitcnt lgkmcnt(2)
	v_pk_add_f32 v[168:169], v[82:83], v[152:153]
	v_add_u32_e32 v82, s19, v188
	v_ashrrev_i32_e32 v83, 31, v82
	v_lshlrev_b32_e32 v184, 16, v160
	v_and_b32_e32 v185, 0xffff0000, v160
	v_lshlrev_b32_e32 v160, 16, v161
	v_and_b32_e32 v161, 0xffff0000, v161
	v_lshlrev_b32_e32 v152, 16, v158
	v_lshlrev_b64 v[82:83], 11, v[82:83]
	v_and_b32_e32 v153, 0xffff0000, v158
	v_lshlrev_b32_e32 v158, 16, v159
	v_and_b32_e32 v159, 0xffff0000, v159
	v_pk_fma_f32 v[74:75], v[160:161], s[6:7], v[74:75] op_sel_hi:[1,0,1]
	v_lshl_add_u64 v[162:163], s[28:29], 0, v[82:83]
	v_pk_fma_f32 v[152:153], v[152:153], s[6:7], v[76:77] op_sel_hi:[1,0,1]
	v_pk_fma_f32 v[76:77], v[158:159], s[6:7], v[78:79] op_sel_hi:[1,0,1]
	v_pk_fma_f32 v[78:79], v[184:185], s[6:7], v[72:73] op_sel_hi:[1,0,1]
	v_mul_f32_e32 v72, v74, v74
	v_lshl_add_u64 v[162:163], v[162:163], 0, s[26:27]
	v_pk_add_f32 v[190:191], v[152:153], v[152:153] op_sel:[0,1] op_sel_hi:[1,0]
	v_pk_add_f32 v[192:193], v[76:77], v[76:77] op_sel:[0,1] op_sel_hi:[1,0]
	v_pk_mul_f32 v[160:161], v[78:79], v[78:79]
	v_pk_fma_f32 v[184:185], v[74:75], v[74:75], v[72:73] op_sel_hi:[1,1,0]
	v_lshlrev_b32_e32 v72, 16, v154
	v_and_b32_e32 v73, 0xffff0000, v154
	v_lshl_add_u64 v[162:163], v[162:163], 0, s[24:25]
	v_pk_mul_f32 v[196:197], v[152:153], v[152:153]
	v_lshlrev_b32_e32 v154, 16, v155
	v_and_b32_e32 v155, 0xffff0000, v155
	v_lshlrev_b32_e32 v200, 16, v156
	v_and_b32_e32 v201, 0xffff0000, v156
	v_lshlrev_b32_e32 v202, 16, v157
	v_and_b32_e32 v203, 0xffff0000, v157
	v_pk_fma_f32 v[68:69], v[72:73], s[6:7], v[68:69] op_sel_hi:[1,0,1]
	v_mov_b32_e32 v191, v160
	v_mov_b32_e32 v193, v161
	v_lshl_add_u64 v[174:175], v[162:163], 0, v[140:141]
	v_pk_mul_f32 v[198:199], v[76:77], v[76:77]
	v_pk_fma_f32 v[70:71], v[154:155], s[6:7], v[70:71] op_sel_hi:[1,0,1]
	v_pk_mul_f32 v[154:155], v[68:69], v[68:69]
	v_pk_fma_f32 v[72:73], v[200:201], s[6:7], v[64:65] op_sel_hi:[1,0,1]
	v_pk_fma_f32 v[64:65], v[202:203], s[6:7], v[66:67] op_sel_hi:[1,0,1]
	v_mov_b32_e32 v202, v78
	v_mov_b32_e32 v203, v196
	v_mov_b32_e32 v196, v79
	v_pk_add_f32 v[160:161], v[190:191], v[192:193]
	v_mov_b32_e32 v184, v141
	s_waitcnt lgkmcnt(1)
	v_pk_add_f32 v[166:167], v[164:165], v[166:167]
	v_mov_b64_e32 v[162:163], v[234:235]
	v_mov_b64_e32 v[164:165], v[236:237]
	v_mov_b64_e32 v[156:157], v[238:239]
	v_mov_b64_e32 v[158:159], v[240:241]
	v_pk_mul_f32 v[174:175], v[70:71], v[70:71]
	v_pk_add_f32 v[196:197], v[202:203], v[196:197]
	v_mov_b32_e32 v202, v74
	v_mov_b32_e32 v203, v198
	v_mov_b32_e32 v198, v75
	v_pk_add_f32 v[160:161], v[160:161], v[184:185]
	v_mov_b32_e32 v184, v68
	v_mov_b32_e32 v185, v154
	v_mov_b32_e32 v154, v69
	v_pk_add_f32 v[198:199], v[202:203], v[198:199]
	v_pk_add_f32 v[154:155], v[184:185], v[154:155]
	v_mov_b32_e32 v184, v70
	v_mov_b32_e32 v185, v174
	v_mov_b32_e32 v174, v71
	v_pk_add_f32 v[196:197], v[196:197], v[198:199]
	v_pk_add_f32 v[174:175], v[184:185], v[174:175]
	v_pk_mul_f32 v[66:67], v[72:73], v[72:73]
	v_pk_add_f32 v[160:161], v[196:197], v[160:161]
	v_pk_add_f32 v[154:155], v[154:155], v[174:175]
	v_pk_mul_f32 v[200:201], v[64:65], v[64:65]
	v_pk_add_f32 v[154:155], v[160:161], v[154:155]
	v_mov_b32_e32 v160, v72
	v_mov_b32_e32 v161, v66
	v_mov_b32_e32 v66, v73
	v_pk_add_f32 v[66:67], v[160:161], v[66:67]
	v_mov_b32_e32 v160, v64
	v_mov_b32_e32 v161, v200
	v_mov_b32_e32 v200, v65
	v_pk_add_f32 v[160:161], v[160:161], v[200:201]
	ds_write_b64 v189, v[166:167]
	v_pk_add_f32 v[66:67], v[66:67], v[160:161]
	v_add_u32_e32 v189, 0x90, v129
	v_pk_add_f32 v[66:67], v[154:155], v[66:67]
	ds_bpermute_b32 v154, v181, v66
	ds_bpermute_b32 v155, v181, v67
	ds_bpermute_b32 v170, v180, v168
	ds_bpermute_b32 v171, v180, v169
	v_lshl_add_u32 v160, v179, 5, s7
	v_cndmask_b32_e32 v206, v183, v160, vcc
	s_waitcnt lgkmcnt(2)
; #define PG8_LAS __attribute__((address_space(3)))
;     __device__ __forceinline__ void fused(f32x4 (&acc)[2][2][4][2], const Unit& u, int wr, int wc, int fr, int fq, PG8_LAS unsigned char* lds, int wid, int lane) const {
;     ...
;         for (int ai = 0; ai < 2; ++ai)
; #pragma unroll
;             for (int m = 0; m < 4; ++m) {
;                 const int rl = ai * 128 + wr * 64 + m * 16 + fr;
;                 const size_t roff = (size_t)(u.pm * 256 + rl) * 1024 + u.pn * 256 + wc * 32 + fq * 8;
;                 float s1 = 0.f, s2 = 0.f;
; #pragma unroll
;                 for (int bj = 0; bj < 2; ++bj) {
;                     float x[8];
;                     if (RES_BF16) ld8f((const bfu*)res + roff + bj * 128, x);
;                     else ld8f32((const float*)res + roff + bj * 128, x);
; #pragma unroll
;                     for (int n = 0; n < 2; ++n) {
;                         f32x4 v = acc[ai][bj][m][n];
;                         v[0] += ALPHA * x[4 * n]; v[1] += ALPHA * x[4 * n + 1]; v[2] += ALPHA * x[4 * n + 2]; v[3] += ALPHA * x[4 * n + 3];
;                         acc[ai][bj][m][n] = v;
;                         s1 += (v[0] + v[1]) + (v[2] + v[3]); s2 += (v[0] * v[0] + v[1] * v[1]) + (v[2] * v[2] + v[3] * v[3]);
;                     }
;                 }
;                 s1 += __shfl_xor(s1, 16); s1 += __shfl_xor(s1, 32); s2 += __shfl_xor(s2, 16); s2 += __shfl_xor(s2, 32);
;                 {
;                     PG8_LAS float* pd = (fq == 0) ? P + (rl * 4 + wc) * 2 : (PG8_LAS float*)(lds + 12288) + tid * 2;
;                     pd[0] = s1; pd[1] = s2;
;                 }
	v_pk_add_f32 v[174:175], v[66:67], v[154:155]
	v_add_u32_e32 v66, s19, v189
	v_ashrrev_i32_e32 v67, 31, v66
	v_lshlrev_b64 v[66:67], 11, v[66:67]
	v_lshl_add_u64 v[160:161], s[28:29], 0, v[66:67]
	v_lshl_add_u64 v[160:161], v[160:161], 0, s[26:27]
	v_lshl_add_u64 v[160:161], v[160:161], 0, s[24:25]
	v_lshl_add_u64 v[160:161], v[160:161], 0, v[140:141]
	s_waitcnt lgkmcnt(0)
	v_pk_add_f32 v[170:171], v[168:169], v[170:171]
	v_mov_b64_e32 v[166:167], v[242:243]
	v_mov_b64_e32 v[168:169], v[244:245]
	ds_bpermute_b32 v184, v180, v174
	ds_bpermute_b32 v185, v180, v175
	ds_write_b64 v206, v[170:171]
	s_waitcnt lgkmcnt(1)
	v_pk_add_f32 v[170:171], v[174:175], v[184:185]
	v_lshlrev_b32_e32 v190, 16, v164
	v_and_b32_e32 v191, 0xffff0000, v164
	v_lshlrev_b32_e32 v164, 16, v165
	v_and_b32_e32 v165, 0xffff0000, v165
	v_lshlrev_b32_e32 v154, 16, v162
	v_and_b32_e32 v155, 0xffff0000, v162
	v_lshlrev_b32_e32 v162, 16, v163
	v_and_b32_e32 v163, 0xffff0000, v163
	v_pk_fma_f32 v[58:59], v[164:165], s[6:7], v[58:59] op_sel_hi:[1,0,1]
	v_pk_fma_f32 v[154:155], v[154:155], s[6:7], v[60:61] op_sel_hi:[1,0,1]
	v_pk_fma_f32 v[60:61], v[162:163], s[6:7], v[62:63] op_sel_hi:[1,0,1]
	v_pk_fma_f32 v[62:63], v[190:191], s[6:7], v[56:57] op_sel_hi:[1,0,1]
	v_mul_f32_e32 v56, v58, v58
	v_pk_fma_f32 v[190:191], v[58:59], v[58:59], v[56:57] op_sel_hi:[1,1,0]
	v_lshlrev_b32_e32 v56, 16, v156
	v_and_b32_e32 v57, 0xffff0000, v156
	v_lshlrev_b32_e32 v200, 16, v158
	v_and_b32_e32 v201, 0xffff0000, v158
	v_lshlrev_b32_e32 v202, 16, v159
	v_and_b32_e32 v203, 0xffff0000, v159
	v_mov_b64_e32 v[158:159], v[246:247]
	v_mov_b64_e32 v[160:161], v[248:249]
	v_pk_mul_f32 v[196:197], v[154:155], v[154:155]
	v_lshlrev_b32_e32 v156, 16, v157
	v_and_b32_e32 v157, 0xffff0000, v157
	v_pk_fma_f32 v[52:53], v[56:57], s[6:7], v[52:53] op_sel_hi:[1,0,1]
	v_pk_add_f32 v[162:163], v[154:155], v[154:155] op_sel:[0,1] op_sel_hi:[1,0]
	v_pk_add_f32 v[192:193], v[60:61], v[60:61] op_sel:[0,1] op_sel_hi:[1,0]
	v_pk_mul_f32 v[198:199], v[60:61], v[60:61]
	v_pk_mul_f32 v[164:165], v[62:63], v[62:63]
	v_pk_fma_f32 v[54:55], v[156:157], s[6:7], v[54:55] op_sel_hi:[1,0,1]
	v_pk_mul_f32 v[156:157], v[52:53], v[52:53]
	v_pk_fma_f32 v[56:57], v[200:201], s[6:7], v[48:49] op_sel_hi:[1,0,1]
	v_pk_fma_f32 v[48:49], v[202:203], s[6:7], v[50:51] op_sel_hi:[1,0,1]
	v_mov_b32_e32 v202, v62
	v_mov_b32_e32 v203, v196
	v_mov_b32_e32 v196, v63
	v_pk_mul_f32 v[204:205], v[54:55], v[54:55]
	v_pk_add_f32 v[196:197], v[202:203], v[196:197]
	v_mov_b32_e32 v202, v58
	v_mov_b32_e32 v203, v198
	v_mov_b32_e32 v198, v59
	v_mov_b32_e32 v163, v164
	v_mov_b32_e32 v193, v165
	v_mov_b32_e32 v164, v52
	v_mov_b32_e32 v165, v156
	v_mov_b32_e32 v156, v53
	v_pk_add_f32 v[198:199], v[202:203], v[198:199]
	v_pk_add_f32 v[162:163], v[162:163], v[192:193]
	v_mov_b32_e32 v190, v141
	v_pk_add_f32 v[156:157], v[164:165], v[156:157]
	v_mov_b32_e32 v164, v54
	v_mov_b32_e32 v165, v204
	v_mov_b32_e32 v204, v55
	v_pk_add_f32 v[196:197], v[196:197], v[198:199]
	v_pk_add_f32 v[162:163], v[162:163], v[190:191]
	v_pk_add_f32 v[164:165], v[164:165], v[204:205]
	v_pk_mul_f32 v[50:51], v[56:57], v[56:57]
	v_pk_add_f32 v[162:163], v[196:197], v[162:163]
	v_pk_add_f32 v[156:157], v[156:157], v[164:165]
	v_pk_mul_f32 v[200:201], v[48:49], v[48:49]
	v_pk_add_f32 v[156:157], v[162:163], v[156:157]
	v_mov_b32_e32 v162, v56
	v_mov_b32_e32 v163, v50
	v_mov_b32_e32 v50, v57
	v_pk_add_f32 v[50:51], v[162:163], v[50:51]
	v_mov_b32_e32 v162, v48
	v_mov_b32_e32 v163, v200
	v_mov_b32_e32 v200, v49
	v_pk_add_f32 v[162:163], v[162:163], v[200:201]
	v_add_u32_e32 v190, 0xa0, v129
	v_pk_add_f32 v[50:51], v[50:51], v[162:163]
	v_lshl_add_u32 v162, v182, 5, s7
	v_pk_add_f32 v[50:51], v[156:157], v[50:51]
	ds_bpermute_b32 v156, v181, v50
	ds_bpermute_b32 v157, v181, v51
	v_cndmask_b32_e32 v191, v183, v162, vcc
	v_lshlrev_b32_e32 v162, 16, v168
	v_and_b32_e32 v163, 0xffff0000, v168
	ds_write_b64 v191, v[170:171]
	s_waitcnt lgkmcnt(1)
	v_pk_add_f32 v[174:175], v[50:51], v[156:157]
	v_lshlrev_b32_e32 v50, 16, v166
	v_and_b32_e32 v51, 0xffff0000, v166
	v_lshlrev_b32_e32 v156, 16, v167
	v_and_b32_e32 v157, 0xffff0000, v167
	v_pk_fma_f32 v[50:51], v[50:51], s[6:7], v[44:45] op_sel_hi:[1,0,1]
	v_pk_fma_f32 v[44:45], v[156:157], s[6:7], v[46:47] op_sel_hi:[1,0,1]
	v_pk_fma_f32 v[46:47], v[162:163], s[6:7], v[40:41] op_sel_hi:[1,0,1]
	v_add_u32_e32 v40, s19, v190
	v_ashrrev_i32_e32 v41, 31, v40
	v_lshlrev_b64 v[156:157], 11, v[40:41]
	v_lshl_add_u64 v[40:41], s[28:29], 0, v[156:157]
	v_lshl_add_u64 v[40:41], v[40:41], 0, s[26:27]
	v_lshl_add_u64 v[40:41], v[40:41], 0, s[24:25]
	v_lshlrev_b32_e32 v166, 16, v169
	v_and_b32_e32 v167, 0xffff0000, v169
	v_lshl_add_u64 v[168:169], v[40:41], 0, v[140:141]
	s_waitcnt vmcnt(0)
	v_mov_b64_e32 v[162:163], v[210:211]
	v_mov_b64_e32 v[164:165], v[212:213]
	v_pk_fma_f32 v[42:43], v[166:167], s[6:7], v[42:43] op_sel_hi:[1,0,1]
	v_pk_add_f32 v[192:193], v[50:51], v[50:51] op_sel:[0,1] op_sel_hi:[1,0]
	v_mul_f32_e32 v40, v42, v42
	v_pk_fma_f32 v[204:205], v[42:43], v[42:43], v[40:41] op_sel_hi:[1,1,0]
	s_waitcnt vmcnt(1)
; #define PG8_LAS __attribute__((address_space(3)))
;     __device__ __forceinline__ void fused(f32x4 (&acc)[2][2][4][2], const Unit& u, int wr, int wc, int fr, int fq, PG8_LAS unsigned char* lds, int wid, int lane) const {
;     ...
;             for (int m = 0; m < 4; ++m) {
;                 const int rl = ai * 128 + wr * 64 + m * 16 + fr;
;                 const size_t roff = (size_t)(u.pm * 256 + rl) * 1024 + u.pn * 256 + wc * 32 + fq * 8;
;                 float s1 = 0.f, s2 = 0.f;
; #pragma unroll
;                 for (int bj = 0; bj < 2; ++bj) {
;                     float x[8];
;                     if (RES_BF16) ld8f((const bfu*)res + roff + bj * 128, x);
;                     else ld8f32((const float*)res + roff + bj * 128, x);
; #pragma unroll
;                     for (int n = 0; n < 2; ++n) {
;                         f32x4 v = acc[ai][bj][m][n];
;                         v[0] += ALPHA * x[4 * n]; v[1] += ALPHA * x[4 * n + 1]; v[2] += ALPHA * x[4 * n + 2]; v[3] += ALPHA * x[4 * n + 3];
;                         acc[ai][bj][m][n] = v;
;                         s1 += (v[0] + v[1]) + (v[2] + v[3]); s2 += (v[0] * v[0] + v[1] * v[1]) + (v[2] * v[2] + v[3] * v[3]);
;                     }
;                 }
;                 s1 += __shfl_xor(s1, 16); s1 += __shfl_xor(s1, 32); s2 += __shfl_xor(s2, 16); s2 += __shfl_xor(s2, 32);
;                 {
;                     PG8_LAS float* pd = (fq == 0) ? P + (rl * 4 + wc) * 2 : (PG8_LAS float*)(lds + 12288) + tid * 2;
;                     pd[0] = s1; pd[1] = s2;
;                 }
	v_lshlrev_b32_e32 v40, 16, v158
	v_and_b32_e32 v41, 0xffff0000, v158
	v_pk_add_f32 v[196:197], v[44:45], v[44:45] op_sel:[0,1] op_sel_hi:[1,0]
	v_pk_mul_f32 v[198:199], v[50:51], v[50:51]
	v_pk_mul_f32 v[202:203], v[46:47], v[46:47]
	v_lshlrev_b32_e32 v158, 16, v159
	v_and_b32_e32 v159, 0xffff0000, v159
	v_pk_fma_f32 v[40:41], v[40:41], s[6:7], v[36:37] op_sel_hi:[1,0,1]
	v_pk_mul_f32 v[200:201], v[44:45], v[44:45]
	v_pk_fma_f32 v[36:37], v[158:159], s[6:7], v[38:39] op_sel_hi:[1,0,1]
	v_pk_mul_f32 v[158:159], v[40:41], v[40:41]
	v_mov_b32_e32 v208, v46
	v_mov_b32_e32 v209, v198
	v_mov_b32_e32 v198, v47
	v_mov_b32_e32 v193, v202
	v_mov_b32_e32 v197, v203
	v_pk_mul_f32 v[206:207], v[36:37], v[36:37]
	v_pk_add_f32 v[198:199], v[208:209], v[198:199]
	v_mov_b32_e32 v208, v42
	v_mov_b32_e32 v209, v200
	v_mov_b32_e32 v200, v43
	v_pk_add_f32 v[192:193], v[192:193], v[196:197]
	v_mov_b32_e32 v196, v40
	v_mov_b32_e32 v197, v158
	v_mov_b32_e32 v158, v41
	v_lshlrev_b32_e32 v166, 16, v160
	v_and_b32_e32 v167, 0xffff0000, v160
	v_pk_add_f32 v[200:201], v[208:209], v[200:201]
	v_mov_b32_e32 v204, v141
	v_pk_add_f32 v[158:159], v[196:197], v[158:159]
	v_mov_b32_e32 v196, v36
	v_mov_b32_e32 v197, v206
	v_mov_b32_e32 v206, v37
	v_lshlrev_b32_e32 v160, 16, v161
	v_and_b32_e32 v161, 0xffff0000, v161
	v_pk_fma_f32 v[38:39], v[166:167], s[6:7], v[32:33] op_sel_hi:[1,0,1]
	v_pk_add_f32 v[198:199], v[198:199], v[200:201]
	v_pk_add_f32 v[192:193], v[192:193], v[204:205]
	v_pk_add_f32 v[196:197], v[196:197], v[206:207]
	v_pk_fma_f32 v[32:33], v[160:161], s[6:7], v[34:35] op_sel_hi:[1,0,1]
	v_pk_mul_f32 v[34:35], v[38:39], v[38:39]
	v_pk_add_f32 v[192:193], v[198:199], v[192:193]
	v_pk_add_f32 v[158:159], v[158:159], v[196:197]
	v_pk_mul_f32 v[160:161], v[32:33], v[32:33]
	v_pk_add_f32 v[158:159], v[192:193], v[158:159]
	v_mov_b32_e32 v192, v38
	v_mov_b32_e32 v193, v34
	v_mov_b32_e32 v34, v39
	v_pk_add_f32 v[34:35], v[192:193], v[34:35]
	v_mov_b32_e32 v192, v32
	v_mov_b32_e32 v193, v160
	v_mov_b32_e32 v160, v33
	v_pk_add_f32 v[160:161], v[192:193], v[160:161]
	s_nop 1
	v_mov_b64_e32 v[166:167], v[214:215]
	v_mov_b64_e32 v[168:169], v[216:217]
	v_pk_add_f32 v[34:35], v[34:35], v[160:161]
	ds_bpermute_b32 v184, v180, v174
	v_pk_add_f32 v[34:35], v[158:159], v[34:35]
	ds_bpermute_b32 v158, v181, v34
	ds_bpermute_b32 v159, v181, v35
	ds_bpermute_b32 v185, v180, v175
	v_add_u32_e32 v191, 0xb0, v129
	v_lshl_add_u32 v160, v188, 5, s7
	v_cndmask_b32_e32 v192, v183, v160, vcc
	s_waitcnt lgkmcnt(1)
	v_pk_add_f32 v[158:159], v[34:35], v[158:159]
	v_add_u32_e32 v34, s19, v191
	v_ashrrev_i32_e32 v35, 31, v34
	ds_bpermute_b32 v170, v180, v158
	ds_bpermute_b32 v171, v180, v159
	v_lshlrev_b64 v[34:35], 11, v[34:35]
	s_waitcnt lgkmcnt(2)
	v_pk_add_f32 v[160:161], v[174:175], v[184:185]
	v_lshl_add_u64 v[174:175], s[28:29], 0, v[34:35]
	v_lshl_add_u64 v[174:175], v[174:175], 0, s[26:27]
	v_lshl_add_u64 v[174:175], v[174:175], 0, s[24:25]
	v_lshl_add_u64 v[174:175], v[174:175], 0, v[140:141]
	v_lshl_add_u32 v140, v189, 5, s7
	s_nop 1
	v_mov_b64_e32 v[196:197], v[218:219]
	v_mov_b64_e32 v[198:199], v[220:221]
	v_cndmask_b32_e32 v140, v183, v140, vcc
	s_waitcnt lgkmcnt(0)
	v_pk_add_f32 v[158:159], v[158:159], v[170:171]
	ds_write_b64 v192, v[160:161]
	ds_write_b64 v140, v[158:159]
	s_waitcnt vmcnt(2)
	v_lshlrev_b32_e32 v158, 16, v162
	v_and_b32_e32 v159, 0xffff0000, v162
	v_lshlrev_b32_e32 v162, 16, v163
	v_and_b32_e32 v163, 0xffff0000, v163
	v_pk_fma_f32 v[160:161], v[158:159], s[6:7], v[28:29] op_sel_hi:[1,0,1]
	v_pk_fma_f32 v[158:159], v[162:163], s[6:7], v[30:31] op_sel_hi:[1,0,1]
	s_nop 1
	v_mov_b64_e32 v[28:29], v[222:223]
	v_mov_b64_e32 v[30:31], v[224:225]
	v_lshlrev_b32_e32 v184, 16, v165
	v_and_b32_e32 v185, 0xffff0000, v165
	v_lshlrev_b32_e32 v170, 16, v164
	v_and_b32_e32 v171, 0xffff0000, v164
	v_pk_fma_f32 v[162:163], v[184:185], s[6:7], v[26:27] op_sel_hi:[1,0,1]
	v_pk_fma_f32 v[164:165], v[170:171], s[6:7], v[24:25] op_sel_hi:[1,0,1]
	v_mul_f32_e32 v24, v162, v162
	v_pk_add_f32 v[192:193], v[160:161], v[160:161] op_sel:[0,1] op_sel_hi:[1,0]
	v_pk_add_f32 v[200:201], v[158:159], v[158:159] op_sel:[0,1] op_sel_hi:[1,0]
	v_pk_mul_f32 v[26:27], v[164:165], v[164:165]
	v_pk_fma_f32 v[170:171], v[162:163], v[162:163], v[24:25] op_sel_hi:[1,1,0]
	v_pk_mul_f32 v[202:203], v[160:161], v[160:161]
	v_mov_b32_e32 v193, v26
	v_mov_b32_e32 v201, v27
	v_pk_mul_f32 v[174:175], v[158:159], v[158:159]
	v_pk_add_f32 v[26:27], v[192:193], v[200:201]
	v_mov_b32_e32 v170, v141
	v_pk_add_f32 v[26:27], v[26:27], v[170:171]
	v_lshl_add_u32 v140, v190, 5, s7
	s_waitcnt vmcnt(2)
; #define PG8_LAS __attribute__((address_space(3)))
;     __device__ __forceinline__ void fused(f32x4 (&acc)[2][2][4][2], const Unit& u, int wr, int wc, int fr, int fq, PG8_LAS unsigned char* lds, int wid, int lane) const {
;     ...
;                 for (int bj = 0; bj < 2; ++bj) {
;                     float x[8];
;                     if (RES_BF16) ld8f((const bfu*)res + roff + bj * 128, x);
;                     else ld8f32((const float*)res + roff + bj * 128, x);
; #pragma unroll
;                     for (int n = 0; n < 2; ++n) {
;                         f32x4 v = acc[ai][bj][m][n];
;                         v[0] += ALPHA * x[4 * n]; v[1] += ALPHA * x[4 * n + 1]; v[2] += ALPHA * x[4 * n + 2]; v[3] += ALPHA * x[4 * n + 3];
;                         acc[ai][bj][m][n] = v;
;                         s1 += (v[0] + v[1]) + (v[2] + v[3]); s2 += (v[0] * v[0] + v[1] * v[1]) + (v[2] * v[2] + v[3] * v[3]);
;                     }
;                 }
;                 s1 += __shfl_xor(s1, 16); s1 += __shfl_xor(s1, 32); s2 += __shfl_xor(s2, 16); s2 += __shfl_xor(s2, 32);
;                 {
;                     PG8_LAS float* pd = (fq == 0) ? P + (rl * 4 + wc) * 2 : (PG8_LAS float*)(lds + 12288) + tid * 2;
;                     pd[0] = s1; pd[1] = s2;
;                 }
;             }
;         __syncthreads();
;         if (tid < 256) {
;             const float a = P[tid * 8] + P[tid * 8 + 2] + P[tid * 8 + 4] + P[tid * 8 + 6], b = P[tid * 8 + 1] + P[tid * 8 + 3] + P[tid * 8 + 5] + P[tid * 8 + 7];
;             const unsigned long long pk = (unsigned long long)__float_as_uint(a) | ((unsigned long long)__float_as_uint(b) << 32);
;             __hip_atomic_store(xch + ((size_t)(u.pm * 256 + tid) * 4 + u.pn), pk, __ATOMIC_RELAXED, __HIP_MEMORY_SCOPE_AGENT);
	v_lshlrev_b32_e32 v24, 16, v166
	v_and_b32_e32 v25, 0xffff0000, v166
	v_lshlrev_b32_e32 v166, 16, v167
	v_and_b32_e32 v167, 0xffff0000, v167
	v_lshlrev_b32_e32 v184, 16, v168
	v_and_b32_e32 v185, 0xffff0000, v168
	v_pk_fma_f32 v[24:25], v[24:25], s[6:7], v[20:21] op_sel_hi:[1,0,1]
	v_pk_fma_f32 v[20:21], v[166:167], s[6:7], v[22:23] op_sel_hi:[1,0,1]
	v_pk_mul_f32 v[166:167], v[24:25], v[24:25]
	v_pk_fma_f32 v[22:23], v[184:185], s[6:7], v[16:17] op_sel_hi:[1,0,1]
	v_mov_b32_e32 v184, v164
	v_mov_b32_e32 v185, v202
	v_mov_b32_e32 v202, v165
	v_pk_mul_f32 v[204:205], v[20:21], v[20:21]
	v_pk_add_f32 v[184:185], v[184:185], v[202:203]
	v_mov_b32_e32 v202, v162
	v_mov_b32_e32 v203, v174
	v_mov_b32_e32 v174, v163
	v_mov_b32_e32 v170, v24
	v_mov_b32_e32 v171, v166
	v_mov_b32_e32 v166, v25
	v_pk_add_f32 v[174:175], v[202:203], v[174:175]
	v_pk_add_f32 v[166:167], v[170:171], v[166:167]
	v_mov_b32_e32 v170, v20
	v_mov_b32_e32 v171, v204
	v_mov_b32_e32 v204, v21
	v_lshlrev_b32_e32 v168, 16, v169
	v_and_b32_e32 v169, 0xffff0000, v169
	v_pk_add_f32 v[174:175], v[184:185], v[174:175]
	v_pk_add_f32 v[170:171], v[170:171], v[204:205]
	v_pk_fma_f32 v[16:17], v[168:169], s[6:7], v[18:19] op_sel_hi:[1,0,1]
	v_pk_mul_f32 v[18:19], v[22:23], v[22:23]
	v_pk_add_f32 v[26:27], v[174:175], v[26:27]
	v_pk_add_f32 v[166:167], v[166:167], v[170:171]
	v_pk_mul_f32 v[168:169], v[16:17], v[16:17]
	v_pk_add_f32 v[26:27], v[26:27], v[166:167]
	v_mov_b32_e32 v166, v22
	v_mov_b32_e32 v167, v18
	v_mov_b32_e32 v18, v23
	v_pk_add_f32 v[18:19], v[166:167], v[18:19]
	v_mov_b32_e32 v166, v16
	v_mov_b32_e32 v167, v168
	v_mov_b32_e32 v168, v17
	v_pk_add_f32 v[166:167], v[166:167], v[168:169]
	s_waitcnt vmcnt(1)
	v_lshlrev_b32_e32 v168, 16, v198
	v_pk_add_f32 v[18:19], v[18:19], v[166:167]
	v_and_b32_e32 v169, 0xffff0000, v198
	v_pk_add_f32 v[184:185], v[26:27], v[18:19]
	v_lshlrev_b32_e32 v18, 16, v196
	v_and_b32_e32 v19, 0xffff0000, v196
	v_lshlrev_b32_e32 v26, 16, v197
	v_and_b32_e32 v27, 0xffff0000, v197
	v_lshlrev_b32_e32 v196, 16, v199
	v_and_b32_e32 v197, 0xffff0000, v199
	v_pk_fma_f32 v[170:171], v[18:19], s[6:7], v[12:13] op_sel_hi:[1,0,1]
	v_pk_fma_f32 v[166:167], v[26:27], s[6:7], v[14:15] op_sel_hi:[1,0,1]
	v_pk_fma_f32 v[174:175], v[168:169], s[6:7], v[8:9] op_sel_hi:[1,0,1]
	v_pk_fma_f32 v[168:169], v[196:197], s[6:7], v[10:11] op_sel_hi:[1,0,1]
	v_pk_add_f32 v[12:13], v[170:171], v[170:171] op_sel:[0,1] op_sel_hi:[1,0]
	v_pk_add_f32 v[14:15], v[166:167], v[166:167] op_sel:[0,1] op_sel_hi:[1,0]
	v_pk_mul_f32 v[8:9], v[174:175], v[174:175]
	v_mul_f32_e32 v10, v168, v168
	s_waitcnt vmcnt(0)
	v_lshlrev_b32_e32 v18, 16, v28
	v_and_b32_e32 v19, 0xffff0000, v28
	v_pk_fma_f32 v[10:11], v[168:169], v[168:169], v[10:11] op_sel_hi:[1,1,0]
	v_lshlrev_b32_e32 v28, 16, v29
	v_and_b32_e32 v29, 0xffff0000, v29
	v_pk_fma_f32 v[26:27], v[18:19], s[6:7], v[4:5] op_sel_hi:[1,0,1]
	v_mov_b32_e32 v13, v8
	v_mov_b32_e32 v15, v9
	v_pk_fma_f32 v[18:19], v[28:29], s[6:7], v[6:7] op_sel_hi:[1,0,1]
	v_pk_mul_f32 v[4:5], v[26:27], v[26:27]
	v_pk_add_f32 v[8:9], v[12:13], v[14:15]
	v_mov_b32_e32 v10, v141
	v_pk_mul_f32 v[198:199], v[170:171], v[170:171]
	v_lshlrev_b32_e32 v196, 16, v30
	v_and_b32_e32 v197, 0xffff0000, v30
	v_pk_mul_f32 v[6:7], v[18:19], v[18:19]
	v_pk_add_f32 v[8:9], v[8:9], v[10:11]
	v_mov_b32_e32 v10, v26
	v_mov_b32_e32 v11, v4
	v_mov_b32_e32 v4, v27
	v_pk_mul_f32 v[200:201], v[166:167], v[166:167]
	v_lshlrev_b32_e32 v202, 16, v31
	v_and_b32_e32 v203, 0xffff0000, v31
	v_pk_fma_f32 v[30:31], v[196:197], s[6:7], v[0:1] op_sel_hi:[1,0,1]
	v_mov_b32_e32 v196, v174
	v_mov_b32_e32 v197, v198
	v_mov_b32_e32 v198, v175
	v_pk_add_f32 v[4:5], v[10:11], v[4:5]
	v_mov_b32_e32 v10, v18
	v_mov_b32_e32 v11, v6
	v_mov_b32_e32 v6, v19
	v_pk_fma_f32 v[28:29], v[202:203], s[6:7], v[2:3] op_sel_hi:[1,0,1]
	v_pk_mul_f32 v[0:1], v[30:31], v[30:31]
	v_pk_add_f32 v[196:197], v[196:197], v[198:199]
	v_mov_b32_e32 v198, v168
	v_mov_b32_e32 v199, v200
	v_mov_b32_e32 v200, v169
	v_pk_add_f32 v[6:7], v[10:11], v[6:7]
	v_pk_mul_f32 v[2:3], v[28:29], v[28:29]
	v_pk_add_f32 v[198:199], v[198:199], v[200:201]
	v_pk_add_f32 v[4:5], v[4:5], v[6:7]
	v_mov_b32_e32 v6, v30
	v_mov_b32_e32 v7, v0
	v_mov_b32_e32 v0, v31
	v_pk_add_f32 v[196:197], v[196:197], v[198:199]
	v_pk_add_f32 v[0:1], v[6:7], v[0:1]
	v_mov_b32_e32 v6, v28
	v_mov_b32_e32 v7, v2
	v_mov_b32_e32 v2, v29
	v_pk_add_f32 v[8:9], v[196:197], v[8:9]
	v_pk_add_f32 v[2:3], v[6:7], v[2:3]
	ds_bpermute_b32 v192, v181, v184
	ds_bpermute_b32 v193, v181, v185
	v_pk_add_f32 v[4:5], v[8:9], v[4:5]
	v_pk_add_f32 v[0:1], v[0:1], v[2:3]
	v_cndmask_b32_e32 v8, v183, v140, vcc
	v_pk_add_f32 v[0:1], v[4:5], v[0:1]
	ds_bpermute_b32 v2, v181, v0
	ds_bpermute_b32 v3, v181, v1
	s_waitcnt lgkmcnt(2)
	v_pk_add_f32 v[4:5], v[184:185], v[192:193]
	ds_bpermute_b32 v6, v180, v4
	ds_bpermute_b32 v7, v180, v5
	s_movk_i32 s6, 0x100
	s_waitcnt lgkmcnt(2)
	v_pk_add_f32 v[0:1], v[0:1], v[2:3]
	ds_bpermute_b32 v2, v180, v0
	ds_bpermute_b32 v3, v180, v1
	s_waitcnt lgkmcnt(2)
	v_pk_add_f32 v[4:5], v[4:5], v[6:7]
	ds_write_b64 v8, v[4:5]
	v_lshl_add_u32 v4, v191, 5, s7
	v_cndmask_b32_e32 v4, v183, v4, vcc
	s_waitcnt lgkmcnt(1)
	v_pk_add_f32 v[0:1], v[0:1], v[2:3]
	ds_write_b64 v4, v[0:1]
	v_or_b32_e32 v0, s19, v172
	v_cmp_gt_u32_e64 s[6:7], s6, v172
	v_ashrrev_i32_e32 v1, 31, v0
	s_waitcnt lgkmcnt(0)
	s_barrier
	s_and_saveexec_b64 s[24:25], s[6:7]
	s_cbranch_execz .LBB0_1050
	v_lshl_add_u32 v6, v172, 5, 0
	ds_read_b128 v[2:5], v6
	ds_read_b128 v[6:9], v6 offset:16
	s_ashr_i32 s21, s20, 31
	s_waitcnt lgkmcnt(1)
	v_add_f32_e32 v2, v2, v4
	v_add_f32_e32 v3, v3, v5
	v_lshlrev_b64 v[4:5], 5, v[0:1]
	s_waitcnt lgkmcnt(0)
	v_add_f32_e32 v2, v2, v6
	v_add_f32_e32 v3, v3, v7
	v_lshl_add_u64 v[4:5], s[22:23], 0, v[4:5]
	v_add_f32_e32 v2, v2, v8
	v_add_f32_e32 v3, v3, v9
	v_lshl_add_u64 v[4:5], s[20:21], 3, v[4:5]
	global_store_dwordx2 v[4:5], v[2:3], off sc1

; #define PG8_LAS __attribute__((address_space(3)))
; __device__ __forceinline__ unsigned xb_add(unsigned* p, unsigned v) { return __hip_atomic_fetch_add(p, v, __ATOMIC_RELAXED, __HIP_MEMORY_SCOPE_AGENT); }
;     __device__ __forceinline__ void fused(f32x4 (&acc)[2][2][4][2], const Unit& u, int wr, int wc, int fr, int fq, PG8_LAS unsigned char* lds, int wid, int lane) const {
;     ...
;         for (int ai = 0; ai < 2; ++ai)
; #pragma unroll
;             for (int m = 0; m < 4; ++m) {
;                 const int rl = ai * 128 + wr * 64 + m * 16 + fr;
;                 const size_t roff = (size_t)(u.pm * 256 + rl) * 1024 + u.pn * 256 + wc * 32 + fq * 8;
;                 float s1 = 0.f, s2 = 0.f;
; #pragma unroll
;                 for (int bj = 0; bj < 2; ++bj) {
;                     float x[8];
;                     if (RES_BF16) ld8f((const bfu*)res + roff + bj * 128, x);
;                     else ld8f32((const float*)res + roff + bj * 128, x);
; #pragma unroll
;                     for (int n = 0; n < 2; ++n) {
;                         f32x4 v = acc[ai][bj][m][n];
;                         v[0] += ALPHA * x[4 * n]; v[1] += ALPHA * x[4 * n + 1]; v[2] += ALPHA * x[4 * n + 2]; v[3] += ALPHA * x[4 * n + 3];
;                         acc[ai][bj][m][n] = v;
;                         s1 += (v[0] + v[1]) + (v[2] + v[3]); s2 += (v[0] * v[0] + v[1] * v[1]) + (v[2] * v[2] + v[3] * v[3]);
;                     }
;                 }
;                 s1 += __shfl_xor(s1, 16); s1 += __shfl_xor(s1, 32); s2 += __shfl_xor(s2, 16); s2 += __shfl_xor(s2, 32);
;                 {
;                     PG8_LAS float* pd = (fq == 0) ? P + (rl * 4 + wc) * 2 : (PG8_LAS float*)(lds + 12288) + tid * 2;
;                     pd[0] = s1; pd[1] = s2;
;                 }
; __device__ __forceinline__ void sample_rows_publish(unsigned* cnt_s, int bid) {
;     asm volatile("s_waitcnt vmcnt(0)" ::: "memory");
;     __syncthreads();
;     if (threadIdx.x == 0) { __builtin_amdgcn_fence(__ATOMIC_RELEASE, "agent"); asm volatile("s_waitcnt vmcnt(0)" ::: "memory"); xb_add(cnt_s + (bid >> 4) * 64, 1u); }
; }
.LBB0_1255:
	s_add_u32 s10, s66, 0x38b80000
	s_addc_u32 s11, s67, 0
	s_lshl_b32 s23, s43, 8
	v_add_u32_e32 v130, s23, v152
	s_lshl_b32 s8, s22, 8
	v_ashrrev_i32_e32 v131, 31, v130
	s_ashr_i32 s9, s8, 31
	v_lshlrev_b64 v[132:133], 11, v[130:131]
	v_lshl_add_u64 v[132:133], s[14:15], 0, v[132:133]
	s_lshl_b64 s[24:25], s[8:9], 1
	s_mov_b32 s21, 0
	v_lshl_add_u64 v[132:133], v[132:133], 0, s[24:25]
	s_lshl_b32 s20, s42, 6
	v_lshl_add_u64 v[132:133], v[132:133], 0, s[20:21]
	v_mov_b32_e32 v129, 0
	v_lshl_add_u64 v[132:133], v[132:133], 0, v[128:129]
	s_barrier
	global_load_dwordx4 v[134:137], v[132:133], off
	global_load_dwordx4 v[138:141], v[132:133], off offset:256
	s_mov_b64 s[98:99], 0x8000
	v_lshl_add_u64 v[250:251], v[132:133], 0, s[98:99]
	global_load_dwordx4 v[196:199], v[250:251], off
	global_load_dwordx4 v[200:203], v[250:251], off offset:256
	s_mov_b64 s[98:99], 0x10000
	v_lshl_add_u64 v[250:251], v[132:133], 0, s[98:99]
	global_load_dwordx4 v[204:207], v[250:251], off
	global_load_dwordx4 v[208:211], v[250:251], off offset:256
	s_mov_b64 s[98:99], 0x18000
	v_lshl_add_u64 v[250:251], v[132:133], 0, s[98:99]
	global_load_dwordx4 v[212:215], v[250:251], off
	global_load_dwordx4 v[216:219], v[250:251], off offset:256
	s_mov_b64 s[98:99], 0x40000
	v_lshl_add_u64 v[250:251], v[132:133], 0, s[98:99]
	global_load_dwordx4 v[220:223], v[250:251], off
	global_load_dwordx4 v[224:227], v[250:251], off offset:256
	s_mov_b64 s[98:99], 0x48000
	v_lshl_add_u64 v[250:251], v[132:133], 0, s[98:99]
	global_load_dwordx4 v[228:231], v[250:251], off
	global_load_dwordx4 v[232:235], v[250:251], off offset:256
	s_mov_b64 s[98:99], 0x50000
	v_lshl_add_u64 v[250:251], v[132:133], 0, s[98:99]
	global_load_dwordx4 v[236:239], v[250:251], off
	global_load_dwordx4 v[240:243], v[250:251], off offset:256
	v_readlane_b32 s98, v252, 6
	v_readlane_b32 s99, v252, 7
	s_nop 3
	s_and_saveexec_b64 s[100:101], s[98:99]
	s_cbranch_execz .Lpub_skip_p10
	s_lshl_b32 s98, s2, 2
	s_andn2_b32 s98, s98, 63
	s_lshl_b32 s98, s98, 2
	s_add_u32 s98, s3, s98
	s_addc_u32 s99, s33, 0
	v_mov_b32_e32 v253, 0
	v_mov_b32_e32 v254, 1
	global_atomic_add v253, v254, s[98:99]
.Lpub_skip_p10:
	s_mov_b64 exec, s[100:101]
	s_mov_b64 s[98:99], 0x58000
	v_lshl_add_u64 v[244:245], v[132:133], 0, s[98:99]
	v_lshl_add_u64 v[248:249], v[132:133], 0, s[98:99]
	global_load_dwordx4 v[244:247], v[244:245], off
	global_load_dwordx4 v[248:251], v[248:249], off offset:256
	v_mbcnt_lo_u32_b32 v132, -1, 0
	v_mbcnt_hi_u32_b32 v142, -1, v132
	v_and_b32_e32 v133, 64, v142
	v_or_b32_e32 v153, 16, v152
	v_xor_b32_e32 v143, 16, v142
	v_add_u32_e32 v145, 64, v133
	v_xor_b32_e32 v144, 32, v142
	v_add_u32_e32 v132, s23, v153
	v_cmp_lt_i32_e32 vcc, v143, v145
	v_ashrrev_i32_e32 v133, 31, v132
	s_mov_b32 s6, 0x3f9837f0
	v_cndmask_b32_e32 v146, v142, v143, vcc
	v_cmp_lt_i32_e32 vcc, v144, v145
	v_lshlrev_b32_e32 v151, 2, v146
	s_waitcnt vmcnt(0)
	v_lshlrev_b32_e32 v154, 16, v135
	v_cndmask_b32_e32 v144, v142, v144, vcc
	v_lshlrev_b64 v[142:143], 11, v[132:133]
	v_lshl_add_u64 v[142:143], s[14:15], 0, v[142:143]
	v_lshl_add_u64 v[142:143], v[142:143], 0, s[24:25]
	v_lshl_add_u64 v[142:143], v[142:143], 0, s[20:21]
	v_lshl_add_u64 v[146:147], v[142:143], 0, v[128:129]
	v_lshlrev_b32_e32 v149, 2, v144
	s_waitcnt vmcnt(0)
	v_mov_b64_e32 v[142:143], v[196:197]
	v_mov_b64_e32 v[144:145], v[198:199]
	v_mov_b64_e32 v[158:159], v[200:201]
	v_mov_b64_e32 v[160:161], v[202:203]
	v_lshlrev_b32_e32 v146, 16, v134
	v_and_b32_e32 v147, 0xffff0000, v134
	v_and_b32_e32 v155, 0xffff0000, v135
	v_lshlrev_b32_e32 v156, 16, v136
	v_and_b32_e32 v157, 0xffff0000, v136
	v_lshlrev_b32_e32 v136, 16, v137
	v_and_b32_e32 v137, 0xffff0000, v137
	v_lshlrev_b32_e32 v162, 16, v138
	v_and_b32_e32 v163, 0xffff0000, v138
	v_lshlrev_b32_e32 v138, 16, v139
	v_and_b32_e32 v139, 0xffff0000, v139
	v_lshlrev_b32_e32 v164, 16, v140
	v_and_b32_e32 v165, 0xffff0000, v140
	v_lshlrev_b32_e32 v140, 16, v141
	v_and_b32_e32 v141, 0xffff0000, v141
	v_pk_fma_f32 v[134:135], v[146:147], s[6:7], v[124:125] op_sel_hi:[1,0,1]
	v_pk_fma_f32 v[126:127], v[154:155], s[6:7], v[126:127] op_sel_hi:[1,0,1]
	v_pk_fma_f32 v[124:125], v[156:157], s[6:7], v[120:121] op_sel_hi:[1,0,1]
	v_pk_fma_f32 v[122:123], v[136:137], s[6:7], v[122:123] op_sel_hi:[1,0,1]
	v_pk_fma_f32 v[120:121], v[162:163], s[6:7], v[116:117] op_sel_hi:[1,0,1]
	v_pk_fma_f32 v[118:119], v[138:139], s[6:7], v[118:119] op_sel_hi:[1,0,1]
	v_pk_fma_f32 v[116:117], v[164:165], s[6:7], v[112:113] op_sel_hi:[1,0,1]
	v_pk_fma_f32 v[112:113], v[140:141], s[6:7], v[114:115] op_sel_hi:[1,0,1]
	v_pk_add_f32 v[114:115], v[134:135], v[134:135] op_sel:[0,1] op_sel_hi:[1,0]
	v_pk_add_f32 v[136:137], v[126:127], v[126:127] op_sel:[0,1] op_sel_hi:[1,0]
	v_pk_mul_f32 v[138:139], v[134:135], v[134:135]
	v_pk_mul_f32 v[140:141], v[126:127], v[126:127]
	v_pk_mul_f32 v[146:147], v[124:125], v[124:125]
	v_mul_f32_e32 v148, v122, v122
	v_mov_b32_e32 v166, v124
	v_mov_b32_e32 v168, v122
	v_pk_fma_f32 v[174:175], v[122:123], v[122:123], v[148:149] op_sel_hi:[1,1,0]
	v_mov_b32_e32 v167, v138
	v_mov_b32_e32 v138, v125
	v_mov_b32_e32 v169, v140
	v_mov_b32_e32 v140, v123
	v_mov_b32_e32 v115, v146
	v_mov_b32_e32 v137, v147
	v_pk_add_f32 v[138:139], v[166:167], v[138:139]
	v_pk_add_f32 v[140:141], v[168:169], v[140:141]
	v_pk_add_f32 v[114:115], v[114:115], v[136:137]
	v_mov_b32_e32 v174, v129
	v_pk_mul_f32 v[154:155], v[120:121], v[120:121]
	v_pk_mul_f32 v[156:157], v[118:119], v[118:119]
	v_pk_add_f32 v[138:139], v[138:139], v[140:141]
	v_pk_add_f32 v[114:115], v[114:115], v[174:175]
	v_mov_b32_e32 v170, v120
	v_mov_b32_e32 v171, v154
	v_mov_b32_e32 v154, v121
	v_pk_add_f32 v[114:115], v[138:139], v[114:115]
	v_mov_b32_e32 v138, v118
	v_mov_b32_e32 v139, v156
	v_mov_b32_e32 v156, v119
	v_pk_add_f32 v[136:137], v[170:171], v[154:155]
	v_pk_add_f32 v[138:139], v[138:139], v[156:157]
	v_pk_mul_f32 v[162:163], v[116:117], v[116:117]
	v_pk_mul_f32 v[164:165], v[112:113], v[112:113]
	v_pk_add_f32 v[136:137], v[136:137], v[138:139]
	v_mov_b32_e32 v138, v112
	v_pk_add_f32 v[114:115], v[114:115], v[136:137]
	v_mov_b32_e32 v136, v116
	v_mov_b32_e32 v137, v162
	v_mov_b32_e32 v162, v117
	v_mov_b32_e32 v139, v164
	v_mov_b32_e32 v164, v113
	v_pk_add_f32 v[136:137], v[136:137], v[162:163]
	v_pk_add_f32 v[138:139], v[138:139], v[164:165]
	v_or_b32_e32 v154, 32, v152
	v_pk_add_f32 v[136:137], v[136:137], v[138:139]
	s_lshl_b32 s7, s42, 3
	v_pk_add_f32 v[114:115], v[114:115], v[136:137]
	ds_bpermute_b32 v136, v151, v114
	ds_bpermute_b32 v137, v151, v115
	s_add_i32 s7, s7, 0
	v_lshl_add_u32 v148, v172, 3, 0
	v_add_u32_e32 v156, 0x3000, v148
	v_lshl_add_u32 v155, v152, 5, s7
	s_waitcnt lgkmcnt(0)
; #define PG8_LAS __attribute__((address_space(3)))
;     __device__ __forceinline__ void fused(f32x4 (&acc)[2][2][4][2], const Unit& u, int wr, int wc, int fr, int fq, PG8_LAS unsigned char* lds, int wid, int lane) const {
;     ...
;             for (int m = 0; m < 4; ++m) {
;                 const int rl = ai * 128 + wr * 64 + m * 16 + fr;
;                 const size_t roff = (size_t)(u.pm * 256 + rl) * 1024 + u.pn * 256 + wc * 32 + fq * 8;
;                 float s1 = 0.f, s2 = 0.f;
; #pragma unroll
;                 for (int bj = 0; bj < 2; ++bj) {
;                     float x[8];
;                     if (RES_BF16) ld8f((const bfu*)res + roff + bj * 128, x);
;                     else ld8f32((const float*)res + roff + bj * 128, x);
; #pragma unroll
;                     for (int n = 0; n < 2; ++n) {
;                         f32x4 v = acc[ai][bj][m][n];
;                         v[0] += ALPHA * x[4 * n]; v[1] += ALPHA * x[4 * n + 1]; v[2] += ALPHA * x[4 * n + 2]; v[3] += ALPHA * x[4 * n + 3];
;                         acc[ai][bj][m][n] = v;
;                         s1 += (v[0] + v[1]) + (v[2] + v[3]); s2 += (v[0] * v[0] + v[1] * v[1]) + (v[2] * v[2] + v[3] * v[3]);
;                     }
;                 }
;                 s1 += __shfl_xor(s1, 16); s1 += __shfl_xor(s1, 32); s2 += __shfl_xor(s2, 16); s2 += __shfl_xor(s2, 32);
;                 {
;                     PG8_LAS float* pd = (fq == 0) ? P + (rl * 4 + wc) * 2 : (PG8_LAS float*)(lds + 12288) + tid * 2;
;                     pd[0] = s1; pd[1] = s2;
;                 }
	v_pk_add_f32 v[138:139], v[114:115], v[136:137]
	v_add_u32_e32 v136, s23, v154
	v_ashrrev_i32_e32 v137, 31, v136
	v_lshlrev_b64 v[140:141], 11, v[136:137]
	v_lshl_add_u64 v[140:141], s[14:15], 0, v[140:141]
	v_lshl_add_u64 v[140:141], v[140:141], 0, s[24:25]
	v_lshl_add_u64 v[140:141], v[140:141], 0, s[20:21]
	v_lshl_add_u64 v[140:141], v[140:141], 0, v[128:129]
	v_mov_b64_e32 v[162:163], v[204:205]
	v_mov_b64_e32 v[164:165], v[206:207]
	s_waitcnt vmcnt(2)
	v_lshlrev_b32_e32 v166, 16, v144
	v_and_b32_e32 v167, 0xffff0000, v144
	v_lshlrev_b32_e32 v144, 16, v145
	v_and_b32_e32 v145, 0xffff0000, v145
	v_lshlrev_b32_e32 v114, 16, v142
	v_and_b32_e32 v115, 0xffff0000, v142
	v_lshlrev_b32_e32 v142, 16, v143
	v_and_b32_e32 v143, 0xffff0000, v143
	v_pk_fma_f32 v[106:107], v[144:145], s[6:7], v[106:107] op_sel_hi:[1,0,1]
	v_pk_fma_f32 v[114:115], v[114:115], s[6:7], v[108:109] op_sel_hi:[1,0,1]
	v_pk_fma_f32 v[110:111], v[142:143], s[6:7], v[110:111] op_sel_hi:[1,0,1]
	v_pk_fma_f32 v[108:109], v[166:167], s[6:7], v[104:105] op_sel_hi:[1,0,1]
	v_mul_f32_e32 v104, v106, v106
	v_pk_add_f32 v[168:169], v[114:115], v[114:115] op_sel:[0,1] op_sel_hi:[1,0]
	v_pk_add_f32 v[170:171], v[110:111], v[110:111] op_sel:[0,1] op_sel_hi:[1,0]
	v_pk_mul_f32 v[144:145], v[108:109], v[108:109]
	v_pk_fma_f32 v[166:167], v[106:107], v[106:107], v[104:105] op_sel_hi:[1,1,0]
	s_waitcnt vmcnt(1)
	v_lshlrev_b32_e32 v104, 16, v158
	v_and_b32_e32 v105, 0xffff0000, v158
	v_pk_mul_f32 v[174:175], v[114:115], v[114:115]
	v_lshlrev_b32_e32 v158, 16, v159
	v_and_b32_e32 v159, 0xffff0000, v159
	v_lshlrev_b32_e32 v178, 16, v160
	v_and_b32_e32 v179, 0xffff0000, v160
	v_pk_fma_f32 v[100:101], v[104:105], s[6:7], v[100:101] op_sel_hi:[1,0,1]
	v_mov_b32_e32 v169, v144
	v_mov_b32_e32 v171, v145
	v_pk_mul_f32 v[176:177], v[110:111], v[110:111]
	v_pk_fma_f32 v[104:105], v[158:159], s[6:7], v[102:103] op_sel_hi:[1,0,1]
	v_pk_mul_f32 v[158:159], v[100:101], v[100:101]
	v_pk_fma_f32 v[102:103], v[178:179], s[6:7], v[96:97] op_sel_hi:[1,0,1]
	v_mov_b32_e32 v178, v108
	v_mov_b32_e32 v179, v174
	v_mov_b32_e32 v174, v109
	v_pk_add_f32 v[144:145], v[168:169], v[170:171]
	v_mov_b32_e32 v166, v129
	v_pk_mul_f32 v[180:181], v[104:105], v[104:105]
	v_pk_add_f32 v[174:175], v[178:179], v[174:175]
	v_mov_b32_e32 v178, v106
	v_mov_b32_e32 v179, v176
	v_mov_b32_e32 v176, v107
	v_pk_add_f32 v[144:145], v[144:145], v[166:167]
	v_mov_b32_e32 v166, v100
	v_mov_b32_e32 v167, v158
	v_mov_b32_e32 v158, v101
	v_pk_add_f32 v[176:177], v[178:179], v[176:177]
	v_pk_add_f32 v[158:159], v[166:167], v[158:159]
	v_mov_b32_e32 v166, v104
	v_mov_b32_e32 v167, v180
	v_mov_b32_e32 v180, v105
	v_lshlrev_b32_e32 v160, 16, v161
	v_and_b32_e32 v161, 0xffff0000, v161
	v_pk_add_f32 v[174:175], v[174:175], v[176:177]
	v_pk_add_f32 v[166:167], v[166:167], v[180:181]
	v_pk_fma_f32 v[96:97], v[160:161], s[6:7], v[98:99] op_sel_hi:[1,0,1]
	v_pk_mul_f32 v[98:99], v[102:103], v[102:103]
	v_pk_add_f32 v[144:145], v[174:175], v[144:145]
	v_pk_add_f32 v[158:159], v[158:159], v[166:167]
	v_pk_mul_f32 v[160:161], v[96:97], v[96:97]
	v_pk_add_f32 v[144:145], v[144:145], v[158:159]
	v_mov_b32_e32 v158, v102
	v_mov_b32_e32 v159, v98
	v_mov_b32_e32 v98, v103
	v_pk_add_f32 v[98:99], v[158:159], v[98:99]
	v_mov_b32_e32 v158, v96
	v_mov_b32_e32 v159, v160
	v_mov_b32_e32 v160, v97
	v_pk_add_f32 v[158:159], v[158:159], v[160:161]
	ds_bpermute_b32 v146, v149, v138
	ds_bpermute_b32 v147, v149, v139
	v_pk_add_f32 v[98:99], v[98:99], v[158:159]
	v_cmp_eq_u32_e32 vcc, 0, v150
	v_pk_add_f32 v[98:99], v[144:145], v[98:99]
	ds_bpermute_b32 v144, v151, v98
	ds_bpermute_b32 v145, v151, v99
	v_cndmask_b32_e32 v157, v156, v155, vcc
	v_or_b32_e32 v155, 48, v152
	s_waitcnt lgkmcnt(2)
	v_pk_add_f32 v[166:167], v[138:139], v[146:147]
	v_add_u32_e32 v138, s23, v155
	v_ashrrev_i32_e32 v139, 31, v138
	s_waitcnt lgkmcnt(0)
	v_pk_add_f32 v[168:169], v[98:99], v[144:145]
	v_lshlrev_b64 v[144:145], 11, v[138:139]
	v_lshl_add_u64 v[144:145], s[14:15], 0, v[144:145]
	v_lshl_add_u64 v[144:145], v[144:145], 0, s[24:25]
	v_lshl_add_u64 v[144:145], v[144:145], 0, s[20:21]
	v_lshl_add_u64 v[158:159], v[144:145], 0, v[128:129]
	v_mov_b64_e32 v[144:145], v[212:213]
	v_mov_b64_e32 v[146:147], v[214:215]
	s_waitcnt vmcnt(1)
	v_lshlrev_b32_e32 v160, 16, v163
	v_mov_b64_e32 v[140:141], v[208:209]
	v_mov_b64_e32 v[142:143], v[210:211]
	v_and_b32_e32 v161, 0xffff0000, v163
	v_pk_fma_f32 v[94:95], v[160:161], s[6:7], v[94:95] op_sel_hi:[1,0,1]
	v_mov_b64_e32 v[158:159], v[216:217]
	v_mov_b64_e32 v[160:161], v[218:219]
	v_lshlrev_b32_e32 v98, 16, v162
	v_and_b32_e32 v99, 0xffff0000, v162
	v_lshlrev_b32_e32 v162, 16, v164
	v_and_b32_e32 v163, 0xffff0000, v164
	v_lshlrev_b32_e32 v164, 16, v165
	v_and_b32_e32 v165, 0xffff0000, v165
	v_pk_fma_f32 v[90:91], v[164:165], s[6:7], v[90:91] op_sel_hi:[1,0,1]
	v_pk_fma_f32 v[98:99], v[98:99], s[6:7], v[92:93] op_sel_hi:[1,0,1]
	v_pk_fma_f32 v[92:93], v[162:163], s[6:7], v[88:89] op_sel_hi:[1,0,1]
	v_mul_f32_e32 v88, v90, v90
	v_pk_add_f32 v[174:175], v[98:99], v[98:99] op_sel:[0,1] op_sel_hi:[1,0]
	v_pk_add_f32 v[176:177], v[94:95], v[94:95] op_sel:[0,1] op_sel_hi:[1,0]
	v_pk_mul_f32 v[162:163], v[92:93], v[92:93]
	v_pk_fma_f32 v[164:165], v[90:91], v[90:91], v[88:89] op_sel_hi:[1,1,0]
	v_pk_mul_f32 v[178:179], v[98:99], v[98:99]
	v_mov_b32_e32 v175, v162
	v_mov_b32_e32 v177, v163
	v_pk_mul_f32 v[180:181], v[94:95], v[94:95]
	v_pk_add_f32 v[162:163], v[174:175], v[176:177]
	v_mov_b32_e32 v164, v129
	v_pk_add_f32 v[162:163], v[162:163], v[164:165]
	ds_write_b64 v157, v[166:167]
	v_add_u32_e32 v157, 0x80, v152
	ds_bpermute_b32 v170, v149, v168
	ds_bpermute_b32 v171, v149, v169
	s_waitcnt vmcnt(2)
; #define PG8_LAS __attribute__((address_space(3)))
;     __device__ __forceinline__ void fused(f32x4 (&acc)[2][2][4][2], const Unit& u, int wr, int wc, int fr, int fq, PG8_LAS unsigned char* lds, int wid, int lane) const {
;     ...
;             for (int m = 0; m < 4; ++m) {
;                 const int rl = ai * 128 + wr * 64 + m * 16 + fr;
;                 const size_t roff = (size_t)(u.pm * 256 + rl) * 1024 + u.pn * 256 + wc * 32 + fq * 8;
;                 float s1 = 0.f, s2 = 0.f;
; #pragma unroll
;                 for (int bj = 0; bj < 2; ++bj) {
;                     float x[8];
;                     if (RES_BF16) ld8f((const bfu*)res + roff + bj * 128, x);
;                     else ld8f32((const float*)res + roff + bj * 128, x);
; #pragma unroll
;                     for (int n = 0; n < 2; ++n) {
;                         f32x4 v = acc[ai][bj][m][n];
;                         v[0] += ALPHA * x[4 * n]; v[1] += ALPHA * x[4 * n + 1]; v[2] += ALPHA * x[4 * n + 2]; v[3] += ALPHA * x[4 * n + 3];
;                         acc[ai][bj][m][n] = v;
;                         s1 += (v[0] + v[1]) + (v[2] + v[3]); s2 += (v[0] * v[0] + v[1] * v[1]) + (v[2] * v[2] + v[3] * v[3]);
;                     }
;                 }
;                 s1 += __shfl_xor(s1, 16); s1 += __shfl_xor(s1, 32); s2 += __shfl_xor(s2, 16); s2 += __shfl_xor(s2, 32);
;                 {
;                     PG8_LAS float* pd = (fq == 0) ? P + (rl * 4 + wc) * 2 : (PG8_LAS float*)(lds + 12288) + tid * 2;
;                     pd[0] = s1; pd[1] = s2;
;                 }
	v_lshlrev_b32_e32 v174, 16, v146
	v_and_b32_e32 v175, 0xffff0000, v146
	s_waitcnt vmcnt(1)
	v_lshlrev_b32_e32 v88, 16, v140
	v_and_b32_e32 v89, 0xffff0000, v140
	v_lshlrev_b32_e32 v140, 16, v141
	v_and_b32_e32 v141, 0xffff0000, v141
	v_lshlrev_b32_e32 v182, 16, v142
	v_and_b32_e32 v183, 0xffff0000, v142
	v_pk_fma_f32 v[84:85], v[88:89], s[6:7], v[84:85] op_sel_hi:[1,0,1]
	v_pk_fma_f32 v[88:89], v[140:141], s[6:7], v[86:87] op_sel_hi:[1,0,1]
	v_pk_mul_f32 v[140:141], v[84:85], v[84:85]
	v_pk_fma_f32 v[86:87], v[182:183], s[6:7], v[80:81] op_sel_hi:[1,0,1]
	v_mov_b32_e32 v182, v92
	v_mov_b32_e32 v183, v178
	v_mov_b32_e32 v178, v93
	v_pk_mul_f32 v[184:185], v[88:89], v[88:89]
	v_pk_add_f32 v[178:179], v[182:183], v[178:179]
	v_mov_b32_e32 v182, v90
	v_mov_b32_e32 v183, v180
	v_mov_b32_e32 v180, v91
	v_mov_b32_e32 v164, v84
	v_mov_b32_e32 v165, v140
	v_mov_b32_e32 v140, v85
	v_pk_add_f32 v[180:181], v[182:183], v[180:181]
	v_pk_add_f32 v[140:141], v[164:165], v[140:141]
	v_mov_b32_e32 v164, v88
	v_mov_b32_e32 v165, v184
	v_mov_b32_e32 v184, v89
	v_lshlrev_b32_e32 v142, 16, v143
	v_and_b32_e32 v143, 0xffff0000, v143
	v_pk_add_f32 v[178:179], v[178:179], v[180:181]
	v_pk_add_f32 v[164:165], v[164:165], v[184:185]
	v_pk_fma_f32 v[80:81], v[142:143], s[6:7], v[82:83] op_sel_hi:[1,0,1]
	v_pk_mul_f32 v[82:83], v[86:87], v[86:87]
	v_pk_add_f32 v[162:163], v[178:179], v[162:163]
	v_pk_add_f32 v[140:141], v[140:141], v[164:165]
	v_pk_mul_f32 v[142:143], v[80:81], v[80:81]
	v_pk_add_f32 v[140:141], v[162:163], v[140:141]
	v_mov_b32_e32 v162, v86
	v_mov_b32_e32 v163, v82
	v_mov_b32_e32 v82, v87
	v_pk_add_f32 v[82:83], v[162:163], v[82:83]
	v_mov_b32_e32 v162, v80
	v_mov_b32_e32 v163, v142
	v_mov_b32_e32 v142, v81
	v_pk_add_f32 v[142:143], v[162:163], v[142:143]
	v_lshlrev_b32_e32 v146, 16, v147
	v_pk_add_f32 v[82:83], v[82:83], v[142:143]
	v_and_b32_e32 v147, 0xffff0000, v147
	v_pk_add_f32 v[82:83], v[140:141], v[82:83]
	ds_bpermute_b32 v140, v151, v82
	ds_bpermute_b32 v141, v151, v83
	v_pk_fma_f32 v[74:75], v[146:147], s[6:7], v[74:75] op_sel_hi:[1,0,1]
	v_lshl_add_u32 v142, v153, 5, s7
	v_cndmask_b32_e32 v173, v156, v142, vcc
	s_waitcnt lgkmcnt(2)
	v_pk_add_f32 v[142:143], v[168:169], v[170:171]
	s_waitcnt lgkmcnt(0)
	v_pk_add_f32 v[166:167], v[82:83], v[140:141]
	v_add_u32_e32 v140, s23, v157
	v_ashrrev_i32_e32 v141, 31, v140
	v_lshlrev_b32_e32 v82, 16, v144
	v_lshlrev_b64 v[162:163], 11, v[140:141]
	v_and_b32_e32 v83, 0xffff0000, v144
	v_lshl_add_u64 v[162:163], s[14:15], 0, v[162:163]
	v_lshlrev_b32_e32 v144, 16, v145
	v_and_b32_e32 v145, 0xffff0000, v145
	v_pk_fma_f32 v[82:83], v[82:83], s[6:7], v[76:77] op_sel_hi:[1,0,1]
	v_pk_fma_f32 v[76:77], v[174:175], s[6:7], v[72:73] op_sel_hi:[1,0,1]
	v_mul_f32_e32 v72, v74, v74
	v_lshl_add_u64 v[162:163], v[162:163], 0, s[24:25]
	v_pk_fma_f32 v[78:79], v[144:145], s[6:7], v[78:79] op_sel_hi:[1,0,1]
	v_pk_fma_f32 v[184:185], v[74:75], v[74:75], v[72:73] op_sel_hi:[1,1,0]
	s_waitcnt vmcnt(0)
	v_lshlrev_b32_e32 v72, 16, v158
	v_and_b32_e32 v73, 0xffff0000, v158
	v_lshl_add_u64 v[162:163], v[162:163], 0, s[20:21]
	v_pk_add_f32 v[176:177], v[82:83], v[82:83] op_sel:[0,1] op_sel_hi:[1,0]
	v_pk_add_f32 v[178:179], v[78:79], v[78:79] op_sel:[0,1] op_sel_hi:[1,0]
	v_pk_mul_f32 v[174:175], v[76:77], v[76:77]
	v_lshlrev_b32_e32 v158, 16, v159
	v_and_b32_e32 v159, 0xffff0000, v159
	v_pk_fma_f32 v[68:69], v[72:73], s[6:7], v[68:69] op_sel_hi:[1,0,1]
	v_lshl_add_u64 v[170:171], v[162:163], 0, v[128:129]
	v_pk_fma_f32 v[72:73], v[158:159], s[6:7], v[70:71] op_sel_hi:[1,0,1]
	v_pk_mul_f32 v[158:159], v[68:69], v[68:69]
	v_mov_b32_e32 v177, v174
	v_mov_b32_e32 v179, v175
	v_mov_b64_e32 v[162:163], v[220:221]
	v_mov_b64_e32 v[164:165], v[222:223]
	v_mov_b64_e32 v[144:145], v[224:225]
	v_mov_b64_e32 v[146:147], v[226:227]
	v_pk_mul_f32 v[180:181], v[82:83], v[82:83]
	v_lshlrev_b32_e32 v186, 16, v160
	v_and_b32_e32 v187, 0xffff0000, v160
	v_pk_mul_f32 v[170:171], v[72:73], v[72:73]
	v_pk_add_f32 v[174:175], v[176:177], v[178:179]
	v_mov_b32_e32 v176, v68
	v_mov_b32_e32 v177, v158
	v_mov_b32_e32 v158, v69
	v_pk_mul_f32 v[182:183], v[78:79], v[78:79]
	v_lshlrev_b32_e32 v160, 16, v161
	v_and_b32_e32 v161, 0xffff0000, v161
	v_pk_fma_f32 v[70:71], v[186:187], s[6:7], v[64:65] op_sel_hi:[1,0,1]
	v_mov_b32_e32 v186, v76
	v_mov_b32_e32 v187, v180
	v_mov_b32_e32 v180, v77
	v_pk_add_f32 v[158:159], v[176:177], v[158:159]
	v_mov_b32_e32 v176, v72
	v_mov_b32_e32 v177, v170
	v_mov_b32_e32 v170, v73
	v_pk_fma_f32 v[64:65], v[160:161], s[6:7], v[66:67] op_sel_hi:[1,0,1]
	v_pk_mul_f32 v[66:67], v[70:71], v[70:71]
	v_pk_add_f32 v[180:181], v[186:187], v[180:181]
	v_mov_b32_e32 v186, v74
	v_mov_b32_e32 v187, v182
	v_mov_b32_e32 v182, v75
	v_pk_add_f32 v[170:171], v[176:177], v[170:171]
	v_pk_mul_f32 v[160:161], v[64:65], v[64:65]
	v_pk_add_f32 v[182:183], v[186:187], v[182:183]
	v_mov_b32_e32 v184, v129
	v_pk_add_f32 v[158:159], v[158:159], v[170:171]
	v_mov_b32_e32 v170, v70
	v_mov_b32_e32 v171, v66
	v_mov_b32_e32 v66, v71
	v_pk_add_f32 v[180:181], v[180:181], v[182:183]
	v_pk_add_f32 v[174:175], v[174:175], v[184:185]
	v_pk_add_f32 v[66:67], v[170:171], v[66:67]
	v_mov_b32_e32 v170, v64
	v_mov_b32_e32 v171, v160
	v_mov_b32_e32 v160, v65
	v_pk_add_f32 v[174:175], v[180:181], v[174:175]
	v_pk_add_f32 v[160:161], v[170:171], v[160:161]
	v_pk_add_f32 v[158:159], v[174:175], v[158:159]
	v_pk_add_f32 v[66:67], v[66:67], v[160:161]
	ds_write_b64 v173, v[142:143]
	v_pk_add_f32 v[66:67], v[158:159], v[66:67]
	ds_bpermute_b32 v158, v151, v66
	ds_bpermute_b32 v159, v151, v67
	v_lshl_add_u32 v142, v154, 5, s7
	v_cndmask_b32_e32 v173, v156, v142, vcc
	ds_bpermute_b32 v168, v149, v166
	ds_bpermute_b32 v169, v149, v167
	s_waitcnt lgkmcnt(2)
; #define PG8_LAS __attribute__((address_space(3)))
;     __device__ __forceinline__ void fused(f32x4 (&acc)[2][2][4][2], const Unit& u, int wr, int wc, int fr, int fq, PG8_LAS unsigned char* lds, int wid, int lane) const {
;     ...
;             for (int m = 0; m < 4; ++m) {
;                 const int rl = ai * 128 + wr * 64 + m * 16 + fr;
;                 const size_t roff = (size_t)(u.pm * 256 + rl) * 1024 + u.pn * 256 + wc * 32 + fq * 8;
;                 float s1 = 0.f, s2 = 0.f;
; #pragma unroll
;                 for (int bj = 0; bj < 2; ++bj) {
;                     float x[8];
;                     if (RES_BF16) ld8f((const bfu*)res + roff + bj * 128, x);
;                     else ld8f32((const float*)res + roff + bj * 128, x);
; #pragma unroll
;                     for (int n = 0; n < 2; ++n) {
;                         f32x4 v = acc[ai][bj][m][n];
;                         v[0] += ALPHA * x[4 * n]; v[1] += ALPHA * x[4 * n + 1]; v[2] += ALPHA * x[4 * n + 2]; v[3] += ALPHA * x[4 * n + 3];
;                         acc[ai][bj][m][n] = v;
;                         s1 += (v[0] + v[1]) + (v[2] + v[3]); s2 += (v[0] * v[0] + v[1] * v[1]) + (v[2] * v[2] + v[3] * v[3]);
;                     }
;                 }
;                 s1 += __shfl_xor(s1, 16); s1 += __shfl_xor(s1, 32); s2 += __shfl_xor(s2, 16); s2 += __shfl_xor(s2, 32);
;                 {
;                     PG8_LAS float* pd = (fq == 0) ? P + (rl * 4 + wc) * 2 : (PG8_LAS float*)(lds + 12288) + tid * 2;
;                     pd[0] = s1; pd[1] = s2;
;                 }
	v_pk_add_f32 v[174:175], v[66:67], v[158:159]
	v_add_u32_e32 v158, 0x90, v152
	v_add_u32_e32 v142, s23, v158
	v_ashrrev_i32_e32 v143, 31, v142
	v_lshlrev_b64 v[160:161], 11, v[142:143]
	v_lshl_add_u64 v[160:161], s[14:15], 0, v[160:161]
	v_lshl_add_u64 v[160:161], v[160:161], 0, s[24:25]
	v_lshl_add_u64 v[160:161], v[160:161], 0, s[20:21]
	v_lshl_add_u64 v[160:161], v[160:161], 0, v[128:129]
	s_waitcnt lgkmcnt(0)
	v_pk_add_f32 v[170:171], v[166:167], v[168:169]
	v_mov_b64_e32 v[166:167], v[228:229]
	v_mov_b64_e32 v[168:169], v[230:231]
	ds_bpermute_b32 v176, v149, v174
	ds_bpermute_b32 v177, v149, v175
	ds_write_b64 v173, v[170:171]
	v_add_u32_e32 v159, 0xa0, v152
	s_waitcnt vmcnt(2)
	v_lshlrev_b32_e32 v178, 16, v164
	v_and_b32_e32 v179, 0xffff0000, v164
	v_lshlrev_b32_e32 v164, 16, v165
	v_and_b32_e32 v165, 0xffff0000, v165
	v_lshlrev_b32_e32 v66, 16, v162
	v_and_b32_e32 v67, 0xffff0000, v162
	v_lshlrev_b32_e32 v162, 16, v163
	v_and_b32_e32 v163, 0xffff0000, v163
	v_pk_fma_f32 v[58:59], v[164:165], s[6:7], v[58:59] op_sel_hi:[1,0,1]
	v_pk_fma_f32 v[66:67], v[66:67], s[6:7], v[60:61] op_sel_hi:[1,0,1]
	v_pk_fma_f32 v[62:63], v[162:163], s[6:7], v[62:63] op_sel_hi:[1,0,1]
	v_pk_fma_f32 v[60:61], v[178:179], s[6:7], v[56:57] op_sel_hi:[1,0,1]
	v_mul_f32_e32 v56, v58, v58
	v_mov_b64_e32 v[160:161], v[232:233]
	v_mov_b64_e32 v[162:163], v[234:235]
	v_pk_add_f32 v[180:181], v[66:67], v[66:67] op_sel:[0,1] op_sel_hi:[1,0]
	v_pk_add_f32 v[182:183], v[62:63], v[62:63] op_sel:[0,1] op_sel_hi:[1,0]
	v_pk_mul_f32 v[164:165], v[60:61], v[60:61]
	v_pk_fma_f32 v[178:179], v[58:59], v[58:59], v[56:57] op_sel_hi:[1,1,0]
	s_waitcnt vmcnt(2)
	v_lshlrev_b32_e32 v56, 16, v144
	v_and_b32_e32 v57, 0xffff0000, v144
	v_pk_mul_f32 v[184:185], v[66:67], v[66:67]
	v_lshlrev_b32_e32 v144, 16, v145
	v_and_b32_e32 v145, 0xffff0000, v145
	v_lshlrev_b32_e32 v188, 16, v146
	v_and_b32_e32 v189, 0xffff0000, v146
	v_pk_fma_f32 v[52:53], v[56:57], s[6:7], v[52:53] op_sel_hi:[1,0,1]
	v_mov_b32_e32 v181, v164
	v_mov_b32_e32 v183, v165
	v_pk_mul_f32 v[186:187], v[62:63], v[62:63]
	v_pk_fma_f32 v[56:57], v[144:145], s[6:7], v[54:55] op_sel_hi:[1,0,1]
	v_pk_mul_f32 v[144:145], v[52:53], v[52:53]
	v_pk_fma_f32 v[54:55], v[188:189], s[6:7], v[48:49] op_sel_hi:[1,0,1]
	v_mov_b32_e32 v188, v60
	v_mov_b32_e32 v189, v184
	v_mov_b32_e32 v184, v61
	v_pk_add_f32 v[164:165], v[180:181], v[182:183]
	v_mov_b32_e32 v178, v129
	v_pk_mul_f32 v[190:191], v[56:57], v[56:57]
	v_pk_add_f32 v[184:185], v[188:189], v[184:185]
	v_mov_b32_e32 v188, v58
	v_mov_b32_e32 v189, v186
	v_mov_b32_e32 v186, v59
	v_pk_add_f32 v[164:165], v[164:165], v[178:179]
	v_mov_b32_e32 v178, v52
	v_mov_b32_e32 v179, v144
	v_mov_b32_e32 v144, v53
	v_pk_add_f32 v[186:187], v[188:189], v[186:187]
	v_pk_add_f32 v[144:145], v[178:179], v[144:145]
	v_mov_b32_e32 v178, v56
	v_mov_b32_e32 v179, v190
	v_mov_b32_e32 v190, v57
	v_lshlrev_b32_e32 v146, 16, v147
	v_and_b32_e32 v147, 0xffff0000, v147
	v_pk_add_f32 v[184:185], v[184:185], v[186:187]
	v_pk_add_f32 v[178:179], v[178:179], v[190:191]
	v_pk_fma_f32 v[48:49], v[146:147], s[6:7], v[50:51] op_sel_hi:[1,0,1]
	v_pk_mul_f32 v[50:51], v[54:55], v[54:55]
	v_pk_add_f32 v[164:165], v[184:185], v[164:165]
	v_pk_add_f32 v[144:145], v[144:145], v[178:179]
	v_pk_mul_f32 v[146:147], v[48:49], v[48:49]
	v_pk_add_f32 v[144:145], v[164:165], v[144:145]
	v_mov_b32_e32 v164, v54
	v_mov_b32_e32 v165, v50
	v_mov_b32_e32 v50, v55
	v_pk_add_f32 v[50:51], v[164:165], v[50:51]
	v_mov_b32_e32 v164, v48
	v_mov_b32_e32 v165, v146
	v_mov_b32_e32 v146, v49
	v_pk_add_f32 v[146:147], v[164:165], v[146:147]
	s_waitcnt vmcnt(1)
	v_lshlrev_b32_e32 v164, 16, v168
	v_pk_add_f32 v[50:51], v[50:51], v[146:147]
	v_lshl_add_u32 v146, v155, 5, s7
	v_pk_add_f32 v[50:51], v[144:145], v[50:51]
	ds_bpermute_b32 v144, v151, v50
	ds_bpermute_b32 v145, v151, v51
	v_cndmask_b32_e32 v173, v156, v146, vcc
	s_waitcnt lgkmcnt(3)
	v_pk_add_f32 v[146:147], v[174:175], v[176:177]
	v_and_b32_e32 v165, 0xffff0000, v168
	v_lshlrev_b32_e32 v168, 16, v169
	s_waitcnt lgkmcnt(0)
	v_pk_add_f32 v[174:175], v[50:51], v[144:145]
	v_lshlrev_b32_e32 v144, 16, v167
	v_and_b32_e32 v145, 0xffff0000, v167
	v_pk_fma_f32 v[46:47], v[144:145], s[6:7], v[46:47] op_sel_hi:[1,0,1]
	v_add_u32_e32 v144, s23, v159
	v_lshlrev_b32_e32 v50, 16, v166
	v_and_b32_e32 v51, 0xffff0000, v166
	v_ashrrev_i32_e32 v145, 31, v144
	v_pk_fma_f32 v[50:51], v[50:51], s[6:7], v[44:45] op_sel_hi:[1,0,1]
	v_pk_fma_f32 v[44:45], v[164:165], s[6:7], v[40:41] op_sel_hi:[1,0,1]
	v_lshlrev_b64 v[40:41], 11, v[144:145]
	v_lshl_add_u64 v[40:41], s[14:15], 0, v[40:41]
	v_lshl_add_u64 v[40:41], v[40:41], 0, s[24:25]
	v_lshl_add_u64 v[40:41], v[40:41], 0, s[20:21]
	v_lshl_add_u64 v[170:171], v[40:41], 0, v[128:129]
	v_mov_b64_e32 v[164:165], v[236:237]
	v_mov_b64_e32 v[166:167], v[238:239]
	v_and_b32_e32 v169, 0xffff0000, v169
	v_pk_fma_f32 v[42:43], v[168:169], s[6:7], v[42:43] op_sel_hi:[1,0,1]
	v_pk_add_f32 v[178:179], v[50:51], v[50:51] op_sel:[0,1] op_sel_hi:[1,0]
	v_mul_f32_e32 v40, v42, v42
	v_pk_fma_f32 v[188:189], v[42:43], v[42:43], v[40:41] op_sel_hi:[1,1,0]
	s_waitcnt vmcnt(1)
; #define PG8_LAS __attribute__((address_space(3)))
;     __device__ __forceinline__ void fused(f32x4 (&acc)[2][2][4][2], const Unit& u, int wr, int wc, int fr, int fq, PG8_LAS unsigned char* lds, int wid, int lane) const {
;     ...
;             for (int m = 0; m < 4; ++m) {
;                 const int rl = ai * 128 + wr * 64 + m * 16 + fr;
;                 const size_t roff = (size_t)(u.pm * 256 + rl) * 1024 + u.pn * 256 + wc * 32 + fq * 8;
;                 float s1 = 0.f, s2 = 0.f;
; #pragma unroll
;                 for (int bj = 0; bj < 2; ++bj) {
;                     float x[8];
;                     if (RES_BF16) ld8f((const bfu*)res + roff + bj * 128, x);
;                     else ld8f32((const float*)res + roff + bj * 128, x);
; #pragma unroll
;                     for (int n = 0; n < 2; ++n) {
;                         f32x4 v = acc[ai][bj][m][n];
;                         v[0] += ALPHA * x[4 * n]; v[1] += ALPHA * x[4 * n + 1]; v[2] += ALPHA * x[4 * n + 2]; v[3] += ALPHA * x[4 * n + 3];
;                         acc[ai][bj][m][n] = v;
;                         s1 += (v[0] + v[1]) + (v[2] + v[3]); s2 += (v[0] * v[0] + v[1] * v[1]) + (v[2] * v[2] + v[3] * v[3]);
;                     }
;                 }
;                 s1 += __shfl_xor(s1, 16); s1 += __shfl_xor(s1, 32); s2 += __shfl_xor(s2, 16); s2 += __shfl_xor(s2, 32);
;                 {
;                     PG8_LAS float* pd = (fq == 0) ? P + (rl * 4 + wc) * 2 : (PG8_LAS float*)(lds + 12288) + tid * 2;
;                     pd[0] = s1; pd[1] = s2;
;                 }
	v_lshlrev_b32_e32 v40, 16, v160
	v_and_b32_e32 v41, 0xffff0000, v160
	v_pk_add_f32 v[180:181], v[46:47], v[46:47] op_sel:[0,1] op_sel_hi:[1,0]
	v_pk_mul_f32 v[182:183], v[50:51], v[50:51]
	v_pk_mul_f32 v[186:187], v[44:45], v[44:45]
	v_lshlrev_b32_e32 v160, 16, v161
	v_and_b32_e32 v161, 0xffff0000, v161
	v_pk_fma_f32 v[40:41], v[40:41], s[6:7], v[36:37] op_sel_hi:[1,0,1]
	v_pk_mul_f32 v[184:185], v[46:47], v[46:47]
	v_pk_fma_f32 v[38:39], v[160:161], s[6:7], v[38:39] op_sel_hi:[1,0,1]
	v_pk_mul_f32 v[160:161], v[40:41], v[40:41]
	v_mov_b32_e32 v192, v44
	v_mov_b32_e32 v193, v182
	v_mov_b32_e32 v182, v45
	v_mov_b32_e32 v179, v186
	v_mov_b32_e32 v181, v187
	v_pk_mul_f32 v[190:191], v[38:39], v[38:39]
	v_pk_add_f32 v[182:183], v[192:193], v[182:183]
	v_mov_b32_e32 v192, v42
	v_mov_b32_e32 v193, v184
	v_mov_b32_e32 v184, v43
	v_pk_add_f32 v[178:179], v[178:179], v[180:181]
	v_mov_b32_e32 v180, v40
	v_mov_b32_e32 v181, v160
	v_mov_b32_e32 v160, v41
	v_lshlrev_b32_e32 v168, 16, v162
	v_and_b32_e32 v169, 0xffff0000, v162
	v_pk_add_f32 v[184:185], v[192:193], v[184:185]
	v_mov_b32_e32 v188, v129
	v_pk_add_f32 v[160:161], v[180:181], v[160:161]
	v_mov_b32_e32 v180, v38
	v_mov_b32_e32 v181, v190
	v_mov_b32_e32 v190, v39
	v_lshlrev_b32_e32 v162, 16, v163
	v_and_b32_e32 v163, 0xffff0000, v163
	v_pk_fma_f32 v[36:37], v[168:169], s[6:7], v[32:33] op_sel_hi:[1,0,1]
	v_pk_add_f32 v[182:183], v[182:183], v[184:185]
	v_pk_add_f32 v[178:179], v[178:179], v[188:189]
	v_pk_add_f32 v[180:181], v[180:181], v[190:191]
	v_pk_fma_f32 v[32:33], v[162:163], s[6:7], v[34:35] op_sel_hi:[1,0,1]
	v_pk_mul_f32 v[34:35], v[36:37], v[36:37]
	v_pk_add_f32 v[178:179], v[182:183], v[178:179]
	v_pk_add_f32 v[160:161], v[160:161], v[180:181]
	v_pk_mul_f32 v[162:163], v[32:33], v[32:33]
	v_pk_add_f32 v[160:161], v[178:179], v[160:161]
	v_mov_b32_e32 v178, v36
	v_mov_b32_e32 v179, v34
	v_mov_b32_e32 v34, v37
	v_pk_add_f32 v[34:35], v[178:179], v[34:35]
	v_mov_b32_e32 v178, v32
	v_mov_b32_e32 v179, v162
	v_mov_b32_e32 v162, v33
	v_pk_add_f32 v[162:163], v[178:179], v[162:163]
	ds_bpermute_b32 v176, v149, v174
	v_pk_add_f32 v[34:35], v[34:35], v[162:163]
	ds_bpermute_b32 v177, v149, v175
	v_pk_add_f32 v[34:35], v[160:161], v[34:35]
	ds_bpermute_b32 v160, v151, v34
	ds_bpermute_b32 v161, v151, v35
	v_mov_b64_e32 v[168:169], v[240:241]
	v_mov_b64_e32 v[170:171], v[242:243]
	ds_write_b64 v173, v[146:147]
	v_lshl_add_u32 v146, v157, 5, s7
	v_cndmask_b32_e32 v173, v156, v146, vcc
	s_waitcnt lgkmcnt(1)
	v_pk_add_f32 v[34:35], v[34:35], v[160:161]
	v_add_u32_e32 v160, 0xb0, v152
	v_add_u32_e32 v146, s23, v160
	v_ashrrev_i32_e32 v147, 31, v146
	v_pk_add_f32 v[162:163], v[174:175], v[176:177]
	ds_bpermute_b32 v178, v149, v34
	ds_bpermute_b32 v179, v149, v35
	v_lshlrev_b64 v[174:175], 11, v[146:147]
	v_lshl_add_u64 v[174:175], s[14:15], 0, v[174:175]
	v_lshl_add_u64 v[174:175], v[174:175], 0, s[24:25]
	v_lshl_add_u64 v[174:175], v[174:175], 0, s[20:21]
	v_lshl_add_u64 v[180:181], v[174:175], 0, v[128:129]
	v_lshl_add_u32 v128, v158, 5, s7
	v_cndmask_b32_e32 v128, v156, v128, vcc
	s_waitcnt lgkmcnt(0)
	v_pk_add_f32 v[34:35], v[34:35], v[178:179]
	s_nop 1
	v_mov_b64_e32 v[174:175], v[244:245]
	v_mov_b64_e32 v[176:177], v[246:247]
	ds_write_b64 v173, v[162:163]
	ds_write_b64 v128, v[34:35]
	s_waitcnt vmcnt(2)
	v_lshlrev_b32_e32 v34, 16, v164
	v_and_b32_e32 v35, 0xffff0000, v164
	v_lshlrev_b32_e32 v162, 16, v165
	v_and_b32_e32 v163, 0xffff0000, v165
	v_pk_fma_f32 v[34:35], v[34:35], s[6:7], v[28:29] op_sel_hi:[1,0,1]
	v_pk_fma_f32 v[28:29], v[162:163], s[6:7], v[30:31] op_sel_hi:[1,0,1]
	s_nop 1
	v_mov_b64_e32 v[162:163], v[248:249]
	v_mov_b64_e32 v[164:165], v[250:251]
	v_lshlrev_b32_e32 v178, 16, v166
	v_and_b32_e32 v179, 0xffff0000, v166
	v_lshlrev_b32_e32 v166, 16, v167
	v_and_b32_e32 v167, 0xffff0000, v167
	v_pk_fma_f32 v[26:27], v[166:167], s[6:7], v[26:27] op_sel_hi:[1,0,1]
	v_pk_fma_f32 v[30:31], v[178:179], s[6:7], v[24:25] op_sel_hi:[1,0,1]
	v_mul_f32_e32 v24, v26, v26
	v_pk_add_f32 v[182:183], v[34:35], v[34:35] op_sel:[0,1] op_sel_hi:[1,0]
	v_pk_add_f32 v[184:185], v[28:29], v[28:29] op_sel:[0,1] op_sel_hi:[1,0]
	v_pk_mul_f32 v[166:167], v[30:31], v[30:31]
	v_pk_fma_f32 v[178:179], v[26:27], v[26:27], v[24:25] op_sel_hi:[1,1,0]
	v_pk_mul_f32 v[186:187], v[34:35], v[34:35]
	v_mov_b32_e32 v183, v166
	v_mov_b32_e32 v185, v167
	v_pk_mul_f32 v[180:181], v[28:29], v[28:29]
	v_pk_add_f32 v[166:167], v[182:183], v[184:185]
	v_mov_b32_e32 v178, v129
	v_pk_add_f32 v[166:167], v[166:167], v[178:179]
	v_lshl_add_u32 v161, v159, 5, s7
	s_waitcnt vmcnt(2)
; #define PG8_LAS __attribute__((address_space(3)))
;     __device__ __forceinline__ void fused(f32x4 (&acc)[2][2][4][2], const Unit& u, int wr, int wc, int fr, int fq, PG8_LAS unsigned char* lds, int wid, int lane) const {
;     ...
;                     for (int n = 0; n < 2; ++n) {
;                         f32x4 v = acc[ai][bj][m][n];
;                         v[0] += ALPHA * x[4 * n]; v[1] += ALPHA * x[4 * n + 1]; v[2] += ALPHA * x[4 * n + 2]; v[3] += ALPHA * x[4 * n + 3];
;                         acc[ai][bj][m][n] = v;
;                         s1 += (v[0] + v[1]) + (v[2] + v[3]); s2 += (v[0] * v[0] + v[1] * v[1]) + (v[2] * v[2] + v[3] * v[3]);
;                     }
;                 }
;                 s1 += __shfl_xor(s1, 16); s1 += __shfl_xor(s1, 32); s2 += __shfl_xor(s2, 16); s2 += __shfl_xor(s2, 32);
;                 {
;                     PG8_LAS float* pd = (fq == 0) ? P + (rl * 4 + wc) * 2 : (PG8_LAS float*)(lds + 12288) + tid * 2;
;                     pd[0] = s1; pd[1] = s2;
;                 }
;             }
;         __syncthreads();
;         if (tid < 256) {
;             const float a = P[tid * 8] + P[tid * 8 + 2] + P[tid * 8 + 4] + P[tid * 8 + 6], b = P[tid * 8 + 1] + P[tid * 8 + 3] + P[tid * 8 + 5] + P[tid * 8 + 7];
;             const unsigned long long pk = (unsigned long long)__float_as_uint(a) | ((unsigned long long)__float_as_uint(b) << 32);
;             __hip_atomic_store(xch + ((size_t)(u.pm * 256 + tid) * 4 + u.pn), pk, __ATOMIC_RELAXED, __HIP_MEMORY_SCOPE_AGENT);
	v_lshlrev_b32_e32 v24, 16, v168
	v_and_b32_e32 v25, 0xffff0000, v168
	v_lshlrev_b32_e32 v168, 16, v169
	v_and_b32_e32 v169, 0xffff0000, v169
	v_lshlrev_b32_e32 v188, 16, v170
	v_and_b32_e32 v189, 0xffff0000, v170
	v_pk_fma_f32 v[24:25], v[24:25], s[6:7], v[20:21] op_sel_hi:[1,0,1]
	v_pk_fma_f32 v[22:23], v[168:169], s[6:7], v[22:23] op_sel_hi:[1,0,1]
	v_pk_mul_f32 v[168:169], v[24:25], v[24:25]
	v_pk_fma_f32 v[20:21], v[188:189], s[6:7], v[16:17] op_sel_hi:[1,0,1]
	v_mov_b32_e32 v188, v30
	v_mov_b32_e32 v189, v186
	v_mov_b32_e32 v186, v31
	v_pk_mul_f32 v[190:191], v[22:23], v[22:23]
	v_pk_add_f32 v[186:187], v[188:189], v[186:187]
	v_mov_b32_e32 v188, v26
	v_mov_b32_e32 v189, v180
	v_mov_b32_e32 v180, v27
	v_mov_b32_e32 v178, v24
	v_mov_b32_e32 v179, v168
	v_mov_b32_e32 v168, v25
	v_pk_add_f32 v[180:181], v[188:189], v[180:181]
	v_pk_add_f32 v[168:169], v[178:179], v[168:169]
	v_mov_b32_e32 v178, v22
	v_mov_b32_e32 v179, v190
	v_mov_b32_e32 v190, v23
	v_lshlrev_b32_e32 v170, 16, v171
	v_and_b32_e32 v171, 0xffff0000, v171
	v_pk_add_f32 v[180:181], v[186:187], v[180:181]
	v_pk_add_f32 v[178:179], v[178:179], v[190:191]
	v_pk_fma_f32 v[16:17], v[170:171], s[6:7], v[18:19] op_sel_hi:[1,0,1]
	v_pk_mul_f32 v[18:19], v[20:21], v[20:21]
	v_pk_add_f32 v[166:167], v[180:181], v[166:167]
	v_pk_add_f32 v[168:169], v[168:169], v[178:179]
	v_pk_mul_f32 v[170:171], v[16:17], v[16:17]
	v_pk_add_f32 v[166:167], v[166:167], v[168:169]
	v_mov_b32_e32 v168, v20
	v_mov_b32_e32 v169, v18
	v_mov_b32_e32 v18, v21
	v_pk_add_f32 v[18:19], v[168:169], v[18:19]
	v_mov_b32_e32 v168, v16
	v_mov_b32_e32 v169, v170
	v_mov_b32_e32 v170, v17
	v_pk_add_f32 v[168:169], v[168:169], v[170:171]
	s_waitcnt vmcnt(1)
	v_lshlrev_b32_e32 v170, 16, v175
	v_pk_add_f32 v[18:19], v[18:19], v[168:169]
	v_and_b32_e32 v171, 0xffff0000, v175
	v_pk_add_f32 v[166:167], v[166:167], v[18:19]
	v_lshlrev_b32_e32 v18, 16, v174
	v_and_b32_e32 v19, 0xffff0000, v174
	v_lshlrev_b32_e32 v174, 16, v176
	v_and_b32_e32 v175, 0xffff0000, v176
	v_lshlrev_b32_e32 v176, 16, v177
	v_and_b32_e32 v177, 0xffff0000, v177
	v_pk_fma_f32 v[18:19], v[18:19], s[6:7], v[12:13] op_sel_hi:[1,0,1]
	v_pk_fma_f32 v[12:13], v[170:171], s[6:7], v[14:15] op_sel_hi:[1,0,1]
	v_pk_fma_f32 v[14:15], v[174:175], s[6:7], v[8:9] op_sel_hi:[1,0,1]
	v_pk_fma_f32 v[8:9], v[176:177], s[6:7], v[10:11] op_sel_hi:[1,0,1]
	s_waitcnt vmcnt(0)
	v_lshlrev_b32_e32 v176, 16, v162
	v_and_b32_e32 v177, 0xffff0000, v162
	v_pk_mul_f32 v[180:181], v[18:19], v[18:19]
	v_mul_f32_e32 v128, v8, v8
	v_lshlrev_b32_e32 v162, 16, v163
	v_and_b32_e32 v163, 0xffff0000, v163
	v_pk_fma_f32 v[4:5], v[176:177], s[6:7], v[4:5] op_sel_hi:[1,0,1]
	v_pk_add_f32 v[170:171], v[18:19], v[18:19] op_sel:[0,1] op_sel_hi:[1,0]
	v_pk_add_f32 v[178:179], v[12:13], v[12:13] op_sel:[0,1] op_sel_hi:[1,0]
	v_pk_mul_f32 v[182:183], v[12:13], v[12:13]
	v_pk_mul_f32 v[10:11], v[14:15], v[14:15]
	v_pk_fma_f32 v[174:175], v[8:9], v[8:9], v[128:129] op_sel_hi:[1,1,0]
	v_pk_fma_f32 v[6:7], v[162:163], s[6:7], v[6:7] op_sel_hi:[1,0,1]
	v_pk_mul_f32 v[162:163], v[4:5], v[4:5]
	v_mov_b32_e32 v186, v14
	v_mov_b32_e32 v187, v180
	v_mov_b32_e32 v180, v15
	v_pk_mul_f32 v[176:177], v[6:7], v[6:7]
	v_pk_add_f32 v[180:181], v[186:187], v[180:181]
	v_mov_b32_e32 v186, v8
	v_mov_b32_e32 v187, v182
	v_mov_b32_e32 v182, v9
	v_mov_b32_e32 v171, v10
	v_mov_b32_e32 v179, v11
	v_mov_b32_e32 v174, v129
	v_mov_b32_e32 v128, v4
	v_mov_b32_e32 v129, v162
	v_mov_b32_e32 v162, v5
	v_lshlrev_b32_e32 v184, 16, v164
	v_and_b32_e32 v185, 0xffff0000, v164
	v_lshlrev_b32_e32 v164, 16, v165
	v_and_b32_e32 v165, 0xffff0000, v165
	v_pk_add_f32 v[182:183], v[186:187], v[182:183]
	v_pk_add_f32 v[10:11], v[170:171], v[178:179]
	v_pk_add_f32 v[128:129], v[128:129], v[162:163]
	v_mov_b32_e32 v162, v6
	v_mov_b32_e32 v163, v176
	v_mov_b32_e32 v176, v7
	v_pk_fma_f32 v[0:1], v[184:185], s[6:7], v[0:1] op_sel_hi:[1,0,1]
	v_pk_fma_f32 v[2:3], v[164:165], s[6:7], v[2:3] op_sel_hi:[1,0,1]
	v_pk_add_f32 v[180:181], v[180:181], v[182:183]
	v_pk_add_f32 v[10:11], v[10:11], v[174:175]
	v_pk_add_f32 v[162:163], v[162:163], v[176:177]
	v_pk_mul_f32 v[164:165], v[0:1], v[0:1]
	v_pk_mul_f32 v[184:185], v[2:3], v[2:3]
	v_pk_add_f32 v[10:11], v[180:181], v[10:11]
	v_pk_add_f32 v[128:129], v[128:129], v[162:163]
	v_mov_b32_e32 v162, v2
	v_pk_add_f32 v[10:11], v[10:11], v[128:129]
	v_mov_b32_e32 v128, v0
	v_mov_b32_e32 v129, v164
	v_mov_b32_e32 v164, v1
	v_mov_b32_e32 v163, v184
	v_mov_b32_e32 v184, v3
	v_pk_add_f32 v[128:129], v[128:129], v[164:165]
	v_pk_add_f32 v[162:163], v[162:163], v[184:185]
	ds_bpermute_b32 v168, v151, v166
	v_pk_add_f32 v[128:129], v[128:129], v[162:163]
	ds_bpermute_b32 v169, v151, v167
	v_pk_add_f32 v[10:11], v[10:11], v[128:129]
	ds_bpermute_b32 v128, v151, v10
	ds_bpermute_b32 v129, v151, v11
	v_cndmask_b32_e32 v151, v156, v161, vcc
	s_waitcnt lgkmcnt(2)
	v_pk_add_f32 v[162:163], v[166:167], v[168:169]
	ds_bpermute_b32 v164, v149, v162
	ds_bpermute_b32 v165, v149, v163
	s_waitcnt lgkmcnt(2)
	v_pk_add_f32 v[10:11], v[10:11], v[128:129]
	ds_bpermute_b32 v128, v149, v10
	ds_bpermute_b32 v129, v149, v11
	v_lshl_add_u32 v149, v160, 5, s7
	s_waitcnt lgkmcnt(2)
	v_pk_add_f32 v[162:163], v[162:163], v[164:165]
	v_cndmask_b32_e32 v149, v156, v149, vcc
	ds_write_b64 v151, v[162:163]
	s_waitcnt lgkmcnt(1)
	v_pk_add_f32 v[10:11], v[10:11], v[128:129]
	ds_write_b64 v149, v[10:11]
	s_movk_i32 s6, 0x100
	v_or_b32_e32 v10, s23, v172
	v_cmp_gt_u32_e64 s[6:7], s6, v172
	v_ashrrev_i32_e32 v11, 31, v10
	s_waitcnt lgkmcnt(0)
	s_barrier
	s_and_saveexec_b64 s[14:15], s[6:7]
	s_cbranch_execz .LBB0_1257
	v_lshl_add_u32 v128, v172, 5, 0
	ds_read_b128 v[162:165], v128
	ds_read_b128 v[166:169], v128 offset:16
	s_ashr_i32 s23, s22, 31
	s_waitcnt lgkmcnt(1)
	v_add_f32_e32 v128, v162, v164
	v_add_f32_e32 v129, v163, v165
	v_lshlrev_b64 v[162:163], 5, v[10:11]
	s_waitcnt lgkmcnt(0)
	v_add_f32_e32 v128, v128, v166
	v_add_f32_e32 v129, v129, v167
	v_lshl_add_u64 v[162:163], s[10:11], 0, v[162:163]
	v_add_f32_e32 v128, v128, v168
	v_add_f32_e32 v129, v129, v169
	v_lshl_add_u64 v[162:163], s[22:23], 3, v[162:163]
	global_store_dwordx2 v[162:163], v[128:129], off sc1
